# Z_H2_E1
# speedup vs baseline: 1.0039x; 1.0008x over previous
;     __device__ bool next(int i, Unit& u) const { if (!base.next(i >> 1, u)) return false; u.sub = i & 1; return true; }
; #define PG8_STAGE(bufoff, gbase, voff) do { _Pragma("unroll") for (int _i = 0; _i < 2; ++_i) \
;         __builtin_amdgcn_global_load_lds((const unsigned*)((const char*)(gbase) + (voff)[_i]), (PG8_LAS unsigned*)(lds + (bufoff) + ldsw + _i * 8192), 16, 0, 0); } while (0)
; #define PG8_LDA(dst, b, h) do { _Pragma("unroll") for (int m = 0; m < 4; ++m) _Pragma("unroll") for (int k = 0; k < 2; ++k) dst[m][k] = *(const PG8_LAS bf16x8*)(lds + PG8_SA(b, h) + aoff + m * 2048 + k * 1024); } while (0)
; #define PG8_LDB(dst, b, h) do { _Pragma("unroll") for (int n = 0; n < 2; ++n) _Pragma("unroll") for (int k = 0; k < 2; ++k) dst[n][k] = *(const PG8_LAS bf16x8*)(lds + PG8_SB(b, h) + boff + n * 2048 + k * 1024); } while (0)
; #define PG8_SCHED __builtin_amdgcn_sched_barrier(0)
;     __host__ __device__ bool next(int i, Unit& u) const {
;         const long L = (long)i * G + c; if (L >= nwg) return false;
;         int wgid = (int)L; { const int q = nwg / NXCD, r = nwg % NXCD, xcd = wgid % NXCD, off = wgid / NXCD; wgid = (xcd < r ? xcd * (q + 1) : r * (q + 1) + (xcd - r) * q) + off; }
;         const int nig = wgm * nN, gid = wgid / nig, fm = gid * wgm, gsz = (nM - fm) < wgm ? (nM - fm) : wgm;
;         u.pm = fm + ((wgid % nig) % gsz); u.pn = (wgid % nig) / gsz; u.sub = 0; return true;
; template <class Epi, class Sched, bool ALIGN_EPI = false, bool SP2 = false, bool DUAL = false>
; __device__ __forceinline__ void gemm_phase(PG8_LAS unsigned char* lds, const Gemm g, const Sched& S, const Epi& E) {
;     ...
;         const bool has_next = S.next(ui + 1, nxt);
;     ...
;             PG8_LDB(B0, 0, 0); PG8_LDB(B1, 0, 1); PG8_SCHED; PG8_LDA(At, 0, 0); PG8_STAGE(PG8_SA(1, 1), a1 + hstep, voffA);
.LBB0_245:
	ds_read_b128 v[80:83], v199
	ds_read_b128 v[84:87], v199 offset:1024
	ds_read_b128 v[88:91], v199 offset:2048
	ds_read_b128 v[92:95], v199 offset:3072
	ds_read_b128 v[144:147], v202
	ds_read_b128 v[148:151], v202 offset:1024
	ds_read_b128 v[152:155], v202 offset:2048
	ds_read_b128 v[156:159], v202 offset:3072
	ds_read_b128 v[208:211], v203
	ds_read_b128 v[212:215], v203 offset:1024
	ds_read_b128 v[216:219], v203 offset:2048
	ds_read_b128 v[220:223], v203 offset:3072
	ds_read_b128 v[232:235], v203 offset:4096
	ds_read_b128 v[236:239], v203 offset:5120
	ds_read_b128 v[240:243], v203 offset:6144
	ds_read_b128 v[244:247], v203 offset:7168
	s_add_i32 s79, s79, 1
	s_mul_i32 s1, s79, s24
	s_mul_hi_u32 s4, s79, s25
	s_add_i32 s4, s4, s1
	s_mul_i32 s1, s79, s25
	s_add_u32 s16, s1, s2
	s_addc_u32 s17, s4, s26
	v_mov_b64_e32 v[0:1], 0x1932
	v_cmp_gt_i64_e32 vcc, s[16:17], v[190:191]
	v_cmp_lt_i64_e64 s[4:5], s[16:17], v[0:1]
	s_cbranch_vccnz .LBB0_251
	s_ashr_i32 s0, s16, 31
	s_lshr_b32 s0, s0, 29
	s_add_i32 s7, s16, s0
	s_and_b32 s0, s7, -8
	s_sub_i32 s9, s16, s0
	s_cmp_gt_i32 s9, 1
	s_mov_b64 s[0:1], -1
	s_cbranch_scc0 .LBB0_248
	s_mul_i32 s0, s9, 0x326
	s_add_i32 s16, s0, 2
	s_mov_b64 s[0:1], 0

; #define PG8_STAGE(bufoff, gbase, voff) do { _Pragma("unroll") for (int _i = 0; _i < 2; ++_i) \
;         __builtin_amdgcn_global_load_lds((const unsigned*)((const char*)(gbase) + (voff)[_i]), (PG8_LAS unsigned*)(lds + (bufoff) + ldsw + _i * 8192), 16, 0, 0); } while (0)
; #define PG8_LDA(dst, b, h) do { _Pragma("unroll") for (int m = 0; m < 4; ++m) _Pragma("unroll") for (int k = 0; k < 2; ++k) dst[m][k] = *(const PG8_LAS bf16x8*)(lds + PG8_SA(b, h) + aoff + m * 2048 + k * 1024); } while (0)
; #define PG8_LDB(dst, b, h) do { _Pragma("unroll") for (int n = 0; n < 2; ++n) _Pragma("unroll") for (int k = 0; k < 2; ++k) dst[n][k] = *(const PG8_LAS bf16x8*)(lds + PG8_SB(b, h) + boff + n * 2048 + k * 1024); } while (0)
; #define PG8_WAIT_V(n) asm volatile("s_waitcnt vmcnt(" #n ")" ::: "memory")
; #define PG8_WAIT_L(n) asm volatile("s_waitcnt lgkmcnt(" #n ")" ::: "memory")
; #define PG8_BAR __builtin_amdgcn_s_barrier()
; #define PG8_SCHED __builtin_amdgcn_sched_barrier(0)
; template <class Epi, class Sched, bool ALIGN_EPI = false, bool SP2 = false, bool DUAL = false>
; __device__ __forceinline__ void gemm_phase(PG8_LAS unsigned char* lds, const Gemm g, const Sched& S, const Epi& E) {
;     ...
;             const char* a2 = last ? nA : cA + (size_t)(t + 2) * kstep; const char* b2 = last ? nB : cB + (size_t)(t + 2) * kstep;
;             const char* a3 = a2 + kstep; const char* b3 = b2 + kstep;
;             if (last && has_next) S.a_ready(nxt);
;             if constexpr (SP2) {
;             PG8_LDB(B0, 0, 0); PG8_LDB(B1, 0, 1); PG8_SCHED; PG8_LDA(At, 0, 0); PG8_STAGE(PG8_SA(1, 1), a1 + hstep, voffA);
;             PG8_WAIT_V(8); PG8_WAIT_L(0); PG8_BAR; PG8_MMA(0, 0, At, B0); PG8_MMA(0, 1, At, B1); PG8_BAR; PG8_SCHED;
;             PG8_LDA(At, 0, 1); PG8_STAGE(PG8_SB(0, 0), b2, voffB); PG8_STAGE(PG8_SB(0, 1), b2 + hstep, voffB); PG8_STAGE(PG8_SA(0, 0), a2, voffA);
;             PG8_WAIT_V(8); PG8_WAIT_L(0); PG8_BAR; PG8_MMA(1, 0, At, B0); PG8_MMA(1, 1, At, B1); PG8_BAR; PG8_SCHED;
;     ...
;         if (!keep)
; #pragma unroll
;         for (int a = 0; a < 2; ++a)
; #pragma unroll
;             for (int b = 0; b < 2; ++b)
; #pragma unroll
;                 for (int m = 0; m < 4; ++m)
; #pragma unroll
;                     for (int n = 0; n < 2; ++n) acc[a][b][m][n] = (f32x4){0.f, 0.f, 0.f, 0.f};
.LBB0_251:
	s_ashr_i32 s87, s86, 31
	s_lshl_b64 s[16:17], s[86:87], 20
	s_add_u32 s92, s58, s16
	s_addc_u32 s93, s59, s17
	s_and_b64 s[16:17], s[4:5], exec
	s_cselect_b32 s7, s93, s11
	s_cselect_b32 s9, s92, s10
	s_ashr_i32 s1, s0, 31
	s_lshl_b64 s[16:17], s[0:1], 20
	s_add_u32 s88, s90, s16
	s_addc_u32 s89, s91, s17
	s_and_b64 s[16:17], s[4:5], exec
	s_cselect_b32 s1, s89, s15
	s_cselect_b32 s45, s88, s14
	s_add_u32 s10, s10, 0x80080
	s_addc_u32 s11, s11, 0
	s_add_u32 s46, s14, 0x100
	s_addc_u32 s47, s15, 0
	s_mov_b32 s48, -2
	s_add_u32 s14, s10, 0xfff80080
	s_addc_u32 s15, s11, -1
	s_cmp_eq_u32 s48, 28
	s_cselect_b32 s17, s7, s15
	s_cselect_b32 s16, s9, s14
	s_cselect_b32 s15, s1, s47
	s_cselect_b32 s14, s45, s46
	v_lshl_add_u64 v[192:193], s[10:11], 0, v[186:187]
	s_add_i32 m0, s19, 0xc000
	s_nop 0
	global_load_lds_dwordx4 v[192:193], off
	v_lshl_add_u64 v[192:193], s[10:11], 0, v[188:189]
	s_add_i32 m0, s19, 0xe000
	s_nop 0
	global_load_lds_dwordx4 v[192:193], off
	s_waitcnt vmcnt(8)
	s_waitcnt lgkmcnt(0)
	s_setprio 1
	s_barrier
	v_mfma_f32_16x16x32_bf16 v[140:143], v[80:83], v[208:211], 0
	v_mfma_f32_16x16x32_bf16 v[132:135], v[88:91], v[208:211], 0
	v_mfma_f32_16x16x32_bf16 v[124:127], v[80:83], v[216:219], 0
	v_mfma_f32_16x16x32_bf16 v[120:123], v[88:91], v[216:219], 0
	v_mfma_f32_16x16x32_bf16 v[108:111], v[80:83], v[232:235], 0
	v_mfma_f32_16x16x32_bf16 v[104:107], v[88:91], v[232:235], 0
	v_mfma_f32_16x16x32_bf16 v[76:79], v[80:83], v[240:243], 0
	v_mfma_f32_16x16x32_bf16 v[72:75], v[88:91], v[240:243], 0
	v_mfma_f32_16x16x32_bf16 v[140:143], v[84:87], v[212:215], v[140:143]
	v_mfma_f32_16x16x32_bf16 v[132:135], v[92:95], v[212:215], v[132:135]
	v_mfma_f32_16x16x32_bf16 v[124:127], v[84:87], v[220:223], v[124:127]
	v_mfma_f32_16x16x32_bf16 v[120:123], v[92:95], v[220:223], v[120:123]
	v_mfma_f32_16x16x32_bf16 v[108:111], v[84:87], v[236:239], v[108:111]
	v_mfma_f32_16x16x32_bf16 v[104:107], v[92:95], v[236:239], v[104:107]
	v_mfma_f32_16x16x32_bf16 v[76:79], v[84:87], v[244:247], v[76:79]
	v_mfma_f32_16x16x32_bf16 v[72:75], v[92:95], v[244:247], v[72:75]
	s_setprio 0
	s_setprio 1
	v_mfma_f32_16x16x32_bf16 v[136:139], v[144:147], v[208:211], 0
	v_mfma_f32_16x16x32_bf16 v[128:131], v[152:155], v[208:211], 0
	v_mfma_f32_16x16x32_bf16 v[116:119], v[144:147], v[216:219], 0
	v_mfma_f32_16x16x32_bf16 v[112:115], v[152:155], v[216:219], 0
	v_mfma_f32_16x16x32_bf16 v[100:103], v[144:147], v[232:235], 0
	v_mfma_f32_16x16x32_bf16 v[96:99], v[152:155], v[232:235], 0
	v_mfma_f32_16x16x32_bf16 v[68:71], v[144:147], v[240:243], 0
	v_mfma_f32_16x16x32_bf16 v[64:67], v[152:155], v[240:243], 0
	v_mfma_f32_16x16x32_bf16 v[136:139], v[148:151], v[212:215], v[136:139]
	v_mfma_f32_16x16x32_bf16 v[128:131], v[156:159], v[212:215], v[128:131]
	v_mfma_f32_16x16x32_bf16 v[116:119], v[148:151], v[220:223], v[116:119]
	v_mfma_f32_16x16x32_bf16 v[112:115], v[156:159], v[220:223], v[112:115]
	v_mfma_f32_16x16x32_bf16 v[100:103], v[148:151], v[236:239], v[100:103]
	v_mfma_f32_16x16x32_bf16 v[96:99], v[156:159], v[236:239], v[96:99]
	v_mfma_f32_16x16x32_bf16 v[68:71], v[148:151], v[244:247], v[68:71]
	v_mfma_f32_16x16x32_bf16 v[64:67], v[156:159], v[244:247], v[64:67]
	s_barrier
	s_setprio 0
	s_add_i32 s49, s31, s18
	v_lshl_add_u64 v[192:193], s[14:15], 0, v[166:167]
	s_mov_b32 m0, s49
	ds_read_b128 v[208:211], v203 offset:16384
	ds_read_b128 v[212:215], v203 offset:17408
	ds_read_b128 v[216:219], v203 offset:18432
	ds_read_b128 v[220:223], v203 offset:19456
	ds_read_b128 v[232:235], v203 offset:20480
	ds_read_b128 v[236:239], v203 offset:21504
	ds_read_b128 v[240:243], v203 offset:22528
	ds_read_b128 v[244:247], v203 offset:23552
	global_load_lds_dwordx4 v[192:193], off
	s_add_i32 m0, s49, 0x2000
	s_add_u32 s50, s14, 0x80000
	v_lshl_add_u64 v[248:249], s[14:15], 0, v[170:171]
	s_addc_u32 s51, s15, 0
	s_add_i32 s49, s34, s18
	global_load_lds_dwordx4 v[248:249], off
	v_lshl_add_u64 v[250:251], s[50:51], 0, v[166:167]
	s_mov_b32 m0, s49
	v_lshl_add_u64 v[252:253], s[16:17], 0, v[168:169]
	global_load_lds_dwordx4 v[250:251], off
	v_lshl_add_u64 v[250:251], s[50:51], 0, v[170:171]
	s_add_i32 m0, s49, 0x2000
	s_nop 0
	global_load_lds_dwordx4 v[250:251], off
	v_lshl_add_u64 v[250:251], s[16:17], 0, v[164:165]
	s_mov_b32 m0, s19
	s_nop 0
	global_load_lds_dwordx4 v[250:251], off
	s_mov_b32 m0, s20
	s_nop 0
	global_load_lds_dwordx4 v[252:253], off
	s_waitcnt vmcnt(8)
	s_waitcnt lgkmcnt(0)
	s_setprio 1
	s_barrier
	v_mfma_f32_16x16x32_bf16 v[60:63], v[80:83], v[208:211], 0
	v_mfma_f32_16x16x32_bf16 v[56:59], v[88:91], v[208:211], 0
	v_mfma_f32_16x16x32_bf16 v[44:47], v[80:83], v[216:219], 0
	v_mfma_f32_16x16x32_bf16 v[40:43], v[88:91], v[216:219], 0
	v_mfma_f32_16x16x32_bf16 v[28:31], v[80:83], v[232:235], 0
	v_mfma_f32_16x16x32_bf16 v[24:27], v[88:91], v[232:235], 0
	v_mfma_f32_16x16x32_bf16 v[12:15], v[80:83], v[240:243], 0
	v_mfma_f32_16x16x32_bf16 v[8:11], v[88:91], v[240:243], 0
	v_mfma_f32_16x16x32_bf16 v[60:63], v[84:87], v[212:215], v[60:63]
	v_mfma_f32_16x16x32_bf16 v[56:59], v[92:95], v[212:215], v[56:59]
	v_mfma_f32_16x16x32_bf16 v[44:47], v[84:87], v[220:223], v[44:47]
	v_mfma_f32_16x16x32_bf16 v[40:43], v[92:95], v[220:223], v[40:43]
	v_mfma_f32_16x16x32_bf16 v[28:31], v[84:87], v[236:239], v[28:31]
	v_mfma_f32_16x16x32_bf16 v[24:27], v[92:95], v[236:239], v[24:27]
	v_mfma_f32_16x16x32_bf16 v[12:15], v[84:87], v[244:247], v[12:15]
	v_mfma_f32_16x16x32_bf16 v[8:11], v[92:95], v[244:247], v[8:11]
	s_setprio 0
	s_setprio 1
	v_mfma_f32_16x16x32_bf16 v[52:55], v[144:147], v[208:211], 0
	v_mfma_f32_16x16x32_bf16 v[48:51], v[152:155], v[208:211], 0
	v_mfma_f32_16x16x32_bf16 v[36:39], v[144:147], v[216:219], 0
	v_mfma_f32_16x16x32_bf16 v[32:35], v[152:155], v[216:219], 0
	v_mfma_f32_16x16x32_bf16 v[20:23], v[144:147], v[232:235], 0
	v_mfma_f32_16x16x32_bf16 v[16:19], v[152:155], v[232:235], 0
	v_mfma_f32_16x16x32_bf16 v[4:7], v[144:147], v[240:243], 0
	v_mfma_f32_16x16x32_bf16 v[0:3], v[152:155], v[240:243], 0
	v_mfma_f32_16x16x32_bf16 v[52:55], v[148:151], v[212:215], v[52:55]
	v_mfma_f32_16x16x32_bf16 v[48:51], v[156:159], v[212:215], v[48:51]
	v_mfma_f32_16x16x32_bf16 v[36:39], v[148:151], v[220:223], v[36:39]
	v_mfma_f32_16x16x32_bf16 v[32:35], v[156:159], v[220:223], v[32:35]
	v_mfma_f32_16x16x32_bf16 v[20:23], v[148:151], v[236:239], v[20:23]
	v_mfma_f32_16x16x32_bf16 v[16:19], v[156:159], v[236:239], v[16:19]
	v_mfma_f32_16x16x32_bf16 v[4:7], v[148:151], v[244:247], v[4:7]
	v_mfma_f32_16x16x32_bf16 v[0:3], v[156:159], v[244:247], v[0:3]
	s_barrier
; #define PG8_STAGE(bufoff, gbase, voff) do { _Pragma("unroll") for (int _i = 0; _i < 2; ++_i) \
;         __builtin_amdgcn_global_load_lds((const unsigned*)((const char*)(gbase) + (voff)[_i]), (PG8_LAS unsigned*)(lds + (bufoff) + ldsw + _i * 8192), 16, 0, 0); } while (0)
; #define PG8_LDA(dst, b, h) do { _Pragma("unroll") for (int m = 0; m < 4; ++m) _Pragma("unroll") for (int k = 0; k < 2; ++k) dst[m][k] = *(const PG8_LAS bf16x8*)(lds + PG8_SA(b, h) + aoff + m * 2048 + k * 1024); } while (0)
; #define PG8_LDB(dst, b, h) do { _Pragma("unroll") for (int n = 0; n < 2; ++n) _Pragma("unroll") for (int k = 0; k < 2; ++k) dst[n][k] = *(const PG8_LAS bf16x8*)(lds + PG8_SB(b, h) + boff + n * 2048 + k * 1024); } while (0)
; #define PG8_MMA(ai, bj, At, Bt) do { __builtin_amdgcn_s_setprio(1); _Pragma("unroll") for (int m = 0; m < 4; ++m) _Pragma("unroll") for (int n = 0; n < 2; ++n) _Pragma("unroll") for (int k = 0; k < 2; ++k) \
;         acc[ai][bj][m][n] = __builtin_amdgcn_mfma_f32_16x16x32_bf16(Bt[n][k], At[m][k], acc[ai][bj][m][n], 0, 0, 0); __builtin_amdgcn_s_setprio(0); } while (0)
; #define PG8_WAIT_V(n) asm volatile("s_waitcnt vmcnt(" #n ")" ::: "memory")
; #define PG8_WAIT_L(n) asm volatile("s_waitcnt lgkmcnt(" #n ")" ::: "memory")
; #define PG8_BAR __builtin_amdgcn_s_barrier()
; #define PG8_SCHED __builtin_amdgcn_sched_barrier(0)
; template <class Epi, class Sched, bool ALIGN_EPI = false, bool SP2 = false, bool DUAL = false>
; __device__ __forceinline__ void gemm_phase(PG8_LAS unsigned char* lds, const Gemm g, const Sched& S, const Epi& E) {
;     ...
;             PG8_LDB(B0, 1, 0); PG8_LDB(B1, 1, 1); PG8_SCHED; PG8_LDA(At, 1, 0); PG8_STAGE(PG8_SA(0, 1), a2 + hstep, voffA);
;             PG8_WAIT_V(8); PG8_WAIT_L(0); PG8_BAR; PG8_MMA(0, 0, At, B0); PG8_MMA(0, 1, At, B1); PG8_BAR; PG8_SCHED;
;             PG8_LDA(At, 1, 1); PG8_STAGE(PG8_SB(1, 0), b3, voffB); PG8_STAGE(PG8_SB(1, 1), b3 + hstep, voffB); PG8_STAGE(PG8_SA(1, 0), a3, voffA);
;             PG8_WAIT_V(8); PG8_WAIT_L(0); PG8_BAR; PG8_MMA(1, 0, At, B0); PG8_MMA(1, 1, At, B1); PG8_BAR; PG8_SCHED;
	s_setprio 0
	s_add_i32 s49, 0, 0x18000
	s_add_i32 s50, 0, 0x1c000
	v_add_u32_e32 v92, s49, v196
	v_add_u32_e32 v156, s50, v196
	ds_read_b128 v[80:83], v92
	ds_read_b128 v[84:87], v92 offset:1024
	ds_read_b128 v[88:91], v92 offset:2048
	ds_read_b128 v[92:95], v92 offset:3072
	ds_read_b128 v[144:147], v156
	ds_read_b128 v[148:151], v156 offset:1024
	ds_read_b128 v[152:155], v156 offset:2048
	ds_read_b128 v[156:159], v156 offset:3072
	s_add_u32 s16, s16, 0x80000
	s_addc_u32 s17, s17, 0
	s_mov_b32 m0, s21
	v_lshl_add_u64 v[228:229], s[16:17], 0, v[164:165]
	ds_read_b128 v[208:211], v203 offset:32768
	ds_read_b128 v[212:215], v203 offset:33792
	ds_read_b128 v[216:219], v203 offset:34816
	ds_read_b128 v[220:223], v203 offset:35840
	ds_read_b128 v[232:235], v203 offset:36864
	ds_read_b128 v[236:239], v203 offset:37888
	ds_read_b128 v[240:243], v203 offset:38912
	ds_read_b128 v[244:247], v203 offset:39936
	global_load_lds_dwordx4 v[228:229], off
	v_lshl_add_u64 v[228:229], s[16:17], 0, v[168:169]
	s_mov_b32 m0, s22
	s_nop 0
	global_load_lds_dwordx4 v[228:229], off
	s_waitcnt vmcnt(8)
	s_waitcnt lgkmcnt(0)
	s_setprio 1
	s_barrier
	v_mfma_f32_16x16x32_bf16 v[140:143], v[80:83], v[208:211], v[140:143]
	v_mfma_f32_16x16x32_bf16 v[132:135], v[88:91], v[208:211], v[132:135]
	v_mfma_f32_16x16x32_bf16 v[124:127], v[80:83], v[216:219], v[124:127]
	v_mfma_f32_16x16x32_bf16 v[120:123], v[88:91], v[216:219], v[120:123]
	v_mfma_f32_16x16x32_bf16 v[108:111], v[80:83], v[232:235], v[108:111]
	v_mfma_f32_16x16x32_bf16 v[104:107], v[88:91], v[232:235], v[104:107]
	v_mfma_f32_16x16x32_bf16 v[76:79], v[80:83], v[240:243], v[76:79]
	v_mfma_f32_16x16x32_bf16 v[72:75], v[88:91], v[240:243], v[72:75]
	v_mfma_f32_16x16x32_bf16 v[140:143], v[84:87], v[212:215], v[140:143]
	v_mfma_f32_16x16x32_bf16 v[132:135], v[92:95], v[212:215], v[132:135]
	v_mfma_f32_16x16x32_bf16 v[124:127], v[84:87], v[220:223], v[124:127]
	v_mfma_f32_16x16x32_bf16 v[120:123], v[92:95], v[220:223], v[120:123]
	v_mfma_f32_16x16x32_bf16 v[108:111], v[84:87], v[236:239], v[108:111]
	v_mfma_f32_16x16x32_bf16 v[104:107], v[92:95], v[236:239], v[104:107]
	v_mfma_f32_16x16x32_bf16 v[76:79], v[84:87], v[244:247], v[76:79]
	v_mfma_f32_16x16x32_bf16 v[72:75], v[92:95], v[244:247], v[72:75]
	s_setprio 0
	s_setprio 1
	v_mfma_f32_16x16x32_bf16 v[136:139], v[144:147], v[208:211], v[136:139]
	v_mfma_f32_16x16x32_bf16 v[128:131], v[152:155], v[208:211], v[128:131]
	v_mfma_f32_16x16x32_bf16 v[116:119], v[144:147], v[216:219], v[116:119]
	v_mfma_f32_16x16x32_bf16 v[112:115], v[152:155], v[216:219], v[112:115]
	v_mfma_f32_16x16x32_bf16 v[100:103], v[144:147], v[232:235], v[100:103]
	v_mfma_f32_16x16x32_bf16 v[96:99], v[152:155], v[232:235], v[96:99]
	v_mfma_f32_16x16x32_bf16 v[68:71], v[144:147], v[240:243], v[68:71]
	v_mfma_f32_16x16x32_bf16 v[64:67], v[152:155], v[240:243], v[64:67]
	v_mfma_f32_16x16x32_bf16 v[136:139], v[148:151], v[212:215], v[136:139]
	v_mfma_f32_16x16x32_bf16 v[128:131], v[156:159], v[212:215], v[128:131]
	v_mfma_f32_16x16x32_bf16 v[116:119], v[148:151], v[220:223], v[116:119]
	v_mfma_f32_16x16x32_bf16 v[112:115], v[156:159], v[220:223], v[112:115]
	v_mfma_f32_16x16x32_bf16 v[100:103], v[148:151], v[236:239], v[100:103]
	v_mfma_f32_16x16x32_bf16 v[96:99], v[156:159], v[236:239], v[96:99]
	v_mfma_f32_16x16x32_bf16 v[68:71], v[148:151], v[244:247], v[68:71]
	v_mfma_f32_16x16x32_bf16 v[64:67], v[156:159], v[244:247], v[64:67]
	s_barrier
	s_setprio 0
	s_add_i32 s16, s49, s18
	v_lshl_add_u64 v[192:193], v[192:193], 0, s[76:77]
	s_mov_b32 m0, s16
	ds_read_b128 v[208:211], v203 offset:49152
	ds_read_b128 v[212:215], v203 offset:50176
	ds_read_b128 v[216:219], v203 offset:51200
	ds_read_b128 v[220:223], v203 offset:52224
	ds_read_b128 v[232:235], v203 offset:53248
	ds_read_b128 v[236:239], v203 offset:54272
	ds_read_b128 v[240:243], v203 offset:55296
	ds_read_b128 v[244:247], v203 offset:56320
	global_load_lds_dwordx4 v[192:193], off
	s_add_i32 m0, s16, 0x2000
	s_add_u32 s14, s14, 0x80080
	v_lshl_add_u64 v[192:193], v[248:249], 0, s[76:77]
	s_addc_u32 s15, s15, 0
	s_add_i32 s16, s50, s18
	global_load_lds_dwordx4 v[192:193], off
	v_lshl_add_u64 v[192:193], s[14:15], 0, v[166:167]
	s_mov_b32 m0, s16
	s_nop 0
	global_load_lds_dwordx4 v[192:193], off
	v_lshl_add_u64 v[192:193], s[14:15], 0, v[170:171]
	s_add_i32 m0, s16, 0x2000
	s_nop 0
	global_load_lds_dwordx4 v[192:193], off
	v_lshl_add_u64 v[192:193], v[250:251], 0, s[76:77]
	s_mov_b32 m0, s27
	s_nop 0
	global_load_lds_dwordx4 v[192:193], off
	v_lshl_add_u64 v[192:193], v[252:253], 0, s[76:77]
	s_mov_b32 m0, s28
	s_nop 0
	global_load_lds_dwordx4 v[192:193], off
	s_waitcnt vmcnt(8)
	s_waitcnt lgkmcnt(0)
	s_setprio 1
	s_barrier
	v_mfma_f32_16x16x32_bf16 v[60:63], v[80:83], v[208:211], v[60:63]
	v_mfma_f32_16x16x32_bf16 v[56:59], v[88:91], v[208:211], v[56:59]
	v_mfma_f32_16x16x32_bf16 v[44:47], v[80:83], v[216:219], v[44:47]
	v_mfma_f32_16x16x32_bf16 v[40:43], v[88:91], v[216:219], v[40:43]
	v_mfma_f32_16x16x32_bf16 v[28:31], v[80:83], v[232:235], v[28:31]
	v_mfma_f32_16x16x32_bf16 v[24:27], v[88:91], v[232:235], v[24:27]
	v_mfma_f32_16x16x32_bf16 v[12:15], v[80:83], v[240:243], v[12:15]
	v_mfma_f32_16x16x32_bf16 v[8:11], v[88:91], v[240:243], v[8:11]
	v_mfma_f32_16x16x32_bf16 v[60:63], v[84:87], v[212:215], v[60:63]
	v_mfma_f32_16x16x32_bf16 v[56:59], v[92:95], v[212:215], v[56:59]
	v_mfma_f32_16x16x32_bf16 v[44:47], v[84:87], v[220:223], v[44:47]
	v_mfma_f32_16x16x32_bf16 v[40:43], v[92:95], v[220:223], v[40:43]
	v_mfma_f32_16x16x32_bf16 v[28:31], v[84:87], v[236:239], v[28:31]
	v_mfma_f32_16x16x32_bf16 v[24:27], v[92:95], v[236:239], v[24:27]
	v_mfma_f32_16x16x32_bf16 v[12:15], v[84:87], v[244:247], v[12:15]
	v_mfma_f32_16x16x32_bf16 v[8:11], v[92:95], v[244:247], v[8:11]
	s_setprio 0
	s_setprio 1
	v_mfma_f32_16x16x32_bf16 v[52:55], v[144:147], v[208:211], v[52:55]
	v_mfma_f32_16x16x32_bf16 v[48:51], v[152:155], v[208:211], v[48:51]
	v_mfma_f32_16x16x32_bf16 v[36:39], v[144:147], v[216:219], v[36:39]
	v_mfma_f32_16x16x32_bf16 v[32:35], v[152:155], v[216:219], v[32:35]
	v_mfma_f32_16x16x32_bf16 v[20:23], v[144:147], v[232:235], v[20:23]
	v_mfma_f32_16x16x32_bf16 v[16:19], v[152:155], v[232:235], v[16:19]
	v_mfma_f32_16x16x32_bf16 v[4:7], v[144:147], v[240:243], v[4:7]
	v_mfma_f32_16x16x32_bf16 v[0:3], v[152:155], v[240:243], v[0:3]
	v_mfma_f32_16x16x32_bf16 v[52:55], v[148:151], v[212:215], v[52:55]
	v_mfma_f32_16x16x32_bf16 v[48:51], v[156:159], v[212:215], v[48:51]
	v_mfma_f32_16x16x32_bf16 v[36:39], v[148:151], v[220:223], v[36:39]
	v_mfma_f32_16x16x32_bf16 v[32:35], v[156:159], v[220:223], v[32:35]
	v_mfma_f32_16x16x32_bf16 v[20:23], v[148:151], v[236:239], v[20:23]
	v_mfma_f32_16x16x32_bf16 v[16:19], v[156:159], v[236:239], v[16:19]
	v_mfma_f32_16x16x32_bf16 v[4:7], v[148:151], v[244:247], v[4:7]
	v_mfma_f32_16x16x32_bf16 v[0:3], v[156:159], v[244:247], v[0:3]
	s_barrier
	s_setprio 0
	s_add_i32 s48, s48, 2
	s_add_u32 s10, s10, 0x100
	s_addc_u32 s11, s11, 0
	s_add_u32 s46, s46, 0x100
	s_addc_u32 s47, s47, 0

;     __device__ bool next(int i, Unit& u) const { if (!base.next(i >> 1, u)) return false; u.sub = i & 1; return true; }
; #define PG8_STAGE(bufoff, gbase, voff) do { _Pragma("unroll") for (int _i = 0; _i < 2; ++_i) \
;         __builtin_amdgcn_global_load_lds((const unsigned*)((const char*)(gbase) + (voff)[_i]), (PG8_LAS unsigned*)(lds + (bufoff) + ldsw + _i * 8192), 16, 0, 0); } while (0)
; #define PG8_LDA(dst, b, h) do { _Pragma("unroll") for (int m = 0; m < 4; ++m) _Pragma("unroll") for (int k = 0; k < 2; ++k) dst[m][k] = *(const PG8_LAS bf16x8*)(lds + PG8_SA(b, h) + aoff + m * 2048 + k * 1024); } while (0)
; #define PG8_LDB(dst, b, h) do { _Pragma("unroll") for (int n = 0; n < 2; ++n) _Pragma("unroll") for (int k = 0; k < 2; ++k) dst[n][k] = *(const PG8_LAS bf16x8*)(lds + PG8_SB(b, h) + boff + n * 2048 + k * 1024); } while (0)
; #define PG8_SCHED __builtin_amdgcn_sched_barrier(0)
;     __host__ __device__ bool next(int i, Unit& u) const {
;         const long L = (long)i * G + c; if (L >= nwg) return false;
;         int wgid = (int)L; { const int q = nwg / NXCD, r = nwg % NXCD, xcd = wgid % NXCD, off = wgid / NXCD; wgid = (xcd < r ? xcd * (q + 1) : r * (q + 1) + (xcd - r) * q) + off; }
; template <class Epi, class Sched, bool ALIGN_EPI = false, bool SP2 = false, bool DUAL = false>
; __device__ __forceinline__ void gemm_phase(PG8_LAS unsigned char* lds, const Gemm g, const Sched& S, const Epi& E) {
;     ...
;         const bool has_next = S.next(ui + 1, nxt);
;     ...
;             PG8_LDB(B0, 0, 0); PG8_LDB(B1, 0, 1); PG8_SCHED; PG8_LDA(At, 0, 0); PG8_STAGE(PG8_SA(1, 1), a1 + hstep, voffA);
.LBB0_889:
	ds_read_b128 v[128:131], v218
	ds_read_b128 v[132:135], v218 offset:1024
	ds_read_b128 v[136:139], v218 offset:2048
	ds_read_b128 v[140:143], v218 offset:3072
	ds_read_b128 v[144:147], v219
	ds_read_b128 v[148:151], v219 offset:1024
	ds_read_b128 v[152:155], v219 offset:2048
	ds_read_b128 v[156:159], v219 offset:3072
	ds_read_b128 v[160:163], v220
	ds_read_b128 v[164:167], v220 offset:1024
	ds_read_b128 v[168:171], v220 offset:2048
	ds_read_b128 v[172:175], v220 offset:3072
	ds_read_b128 v[196:199], v220 offset:4096
	ds_read_b128 v[202:205], v220 offset:5120
	ds_read_b128 v[206:209], v220 offset:6144
	ds_read_b128 v[232:235], v220 offset:7168
	s_add_i32 s51, s51, 1
	s_mul_i32 s6, s51, s42
	s_mul_hi_u32 s7, s51, s46
	s_add_i32 s7, s7, s6
	s_mul_i32 s6, s51, s46
	s_add_u32 s18, s6, s2
	s_addc_u32 s19, s7, s43
	v_cmp_gt_i64_e32 vcc, s[18:19], v[194:195]
	v_cmp_lt_i64_e64 s[6:7], s[18:19], v[192:193]
	s_cbranch_vccnz .LBB0_895
	s_ashr_i32 s19, s18, 31
	s_lshr_b32 s19, s19, 29
	s_add_i32 s40, s18, s19
	s_and_b32 s19, s40, -8
	s_sub_i32 s41, s18, s19
	s_cmp_gt_i32 s41, -1
	s_mov_b64 s[18:19], -1
	s_cbranch_scc0 .LBB0_892
	s_lshl_b32 s60, s41, 7
	s_mov_b64 s[18:19], 0

; #define PG8_STAGE(bufoff, gbase, voff) do { _Pragma("unroll") for (int _i = 0; _i < 2; ++_i) \
;         __builtin_amdgcn_global_load_lds((const unsigned*)((const char*)(gbase) + (voff)[_i]), (PG8_LAS unsigned*)(lds + (bufoff) + ldsw + _i * 8192), 16, 0, 0); } while (0)
; #define PG8_LDA(dst, b, h) do { _Pragma("unroll") for (int m = 0; m < 4; ++m) _Pragma("unroll") for (int k = 0; k < 2; ++k) dst[m][k] = *(const PG8_LAS bf16x8*)(lds + PG8_SA(b, h) + aoff + m * 2048 + k * 1024); } while (0)
; #define PG8_LDB(dst, b, h) do { _Pragma("unroll") for (int n = 0; n < 2; ++n) _Pragma("unroll") for (int k = 0; k < 2; ++k) dst[n][k] = *(const PG8_LAS bf16x8*)(lds + PG8_SB(b, h) + boff + n * 2048 + k * 1024); } while (0)
; #define PG8_WAIT_V(n) asm volatile("s_waitcnt vmcnt(" #n ")" ::: "memory")
; #define PG8_WAIT_L(n) asm volatile("s_waitcnt lgkmcnt(" #n ")" ::: "memory")
; #define PG8_BAR __builtin_amdgcn_s_barrier()
; #define PG8_SCHED __builtin_amdgcn_sched_barrier(0)
; template <class Epi, class Sched, bool ALIGN_EPI = false, bool SP2 = false, bool DUAL = false>
; __device__ __forceinline__ void gemm_phase(PG8_LAS unsigned char* lds, const Gemm g, const Sched& S, const Epi& E) {
;     ...
;             const char* a2 = last ? nA : cA + (size_t)(t + 2) * kstep; const char* b2 = last ? nB : cB + (size_t)(t + 2) * kstep;
;             const char* a3 = a2 + kstep; const char* b3 = b2 + kstep;
;             if (last && has_next) S.a_ready(nxt);
;             if constexpr (SP2) {
;             PG8_LDB(B0, 0, 0); PG8_LDB(B1, 0, 1); PG8_SCHED; PG8_LDA(At, 0, 0); PG8_STAGE(PG8_SA(1, 1), a1 + hstep, voffA);
;             PG8_WAIT_V(8); PG8_WAIT_L(0); PG8_BAR; PG8_MMA(0, 0, At, B0); PG8_MMA(0, 1, At, B1); PG8_BAR; PG8_SCHED;
;             PG8_LDA(At, 0, 1); PG8_STAGE(PG8_SB(0, 0), b2, voffB); PG8_STAGE(PG8_SB(0, 1), b2 + hstep, voffB); PG8_STAGE(PG8_SA(0, 0), a2, voffA);
;             PG8_WAIT_V(8); PG8_WAIT_L(0); PG8_BAR; PG8_MMA(1, 0, At, B0); PG8_MMA(1, 1, At, B1); PG8_BAR; PG8_SCHED;
;     ...
;         if (!keep)
; #pragma unroll
;         for (int a = 0; a < 2; ++a)
; #pragma unroll
;             for (int b = 0; b < 2; ++b)
; #pragma unroll
;                 for (int m = 0; m < 4; ++m)
; #pragma unroll
;                     for (int n = 0; n < 2; ++n) acc[a][b][m][n] = (f32x4){0.f, 0.f, 0.f, 0.f};
.LBB0_895:
	s_ashr_i32 s61, s60, 31
	s_lshl_b64 s[18:19], s[60:61], 20
	s_add_u32 s62, s10, s18
	s_addc_u32 s63, s11, s19
	s_and_b64 s[18:19], s[6:7], exec
	s_cselect_b32 s18, s63, s17
	s_cselect_b32 s19, s62, s16
	s_ashr_i32 s41, s40, 31
	s_lshl_b64 s[64:65], s[40:41], 20
	s_add_u32 s64, s12, s64
	s_addc_u32 s65, s13, s65
	s_and_b64 s[68:69], s[6:7], exec
	s_cselect_b32 s41, s65, s15
	s_cselect_b32 s61, s64, s14
	s_add_u32 s68, s16, 0x80080
	s_addc_u32 s69, s17, 0
	s_add_u32 s67, s14, 0x100
	s_addc_u32 s70, s15, 0
	s_mov_b32 s71, -2
	s_waitcnt lgkmcnt(0)
	s_add_u32 s14, s68, 0xfff80080
	s_addc_u32 s15, s69, -1
	s_cmp_eq_u32 s71, 28
	s_cselect_b32 s17, s18, s15
	s_cselect_b32 s16, s19, s14
	s_cselect_b32 s15, s41, s70
	s_cselect_b32 s14, s61, s67
	v_lshl_add_u64 v[222:223], s[68:69], 0, v[188:189]
	s_add_i32 m0, s27, 0xc000
	s_nop 0
	global_load_lds_dwordx4 v[222:223], off
	v_lshl_add_u64 v[222:223], s[68:69], 0, v[190:191]
	s_add_i32 m0, s27, 0xe000
	s_nop 0
	global_load_lds_dwordx4 v[222:223], off
	s_waitcnt vmcnt(8)
	s_waitcnt lgkmcnt(0)
	s_setprio 1
	s_barrier
	v_mfma_f32_16x16x32_bf16 v[124:127], v[128:131], v[160:163], 0
	v_mfma_f32_16x16x32_bf16 v[120:123], v[136:139], v[160:163], 0
	v_mfma_f32_16x16x32_bf16 v[108:111], v[128:131], v[168:171], 0
	v_mfma_f32_16x16x32_bf16 v[104:107], v[136:139], v[168:171], 0
	v_mfma_f32_16x16x32_bf16 v[92:95], v[128:131], v[196:199], 0
	v_mfma_f32_16x16x32_bf16 v[88:91], v[136:139], v[196:199], 0
	v_mfma_f32_16x16x32_bf16 v[76:79], v[128:131], v[206:209], 0
	v_mfma_f32_16x16x32_bf16 v[72:75], v[136:139], v[206:209], 0
	v_mfma_f32_16x16x32_bf16 v[124:127], v[132:135], v[164:167], v[124:127]
	v_mfma_f32_16x16x32_bf16 v[120:123], v[140:143], v[164:167], v[120:123]
	v_mfma_f32_16x16x32_bf16 v[108:111], v[132:135], v[172:175], v[108:111]
	v_mfma_f32_16x16x32_bf16 v[104:107], v[140:143], v[172:175], v[104:107]
	v_mfma_f32_16x16x32_bf16 v[92:95], v[132:135], v[202:205], v[92:95]
	v_mfma_f32_16x16x32_bf16 v[88:91], v[140:143], v[202:205], v[88:91]
	v_mfma_f32_16x16x32_bf16 v[76:79], v[132:135], v[232:235], v[76:79]
	v_mfma_f32_16x16x32_bf16 v[72:75], v[140:143], v[232:235], v[72:75]
	s_setprio 0
	s_setprio 1
	v_mfma_f32_16x16x32_bf16 v[116:119], v[144:147], v[160:163], 0
	v_mfma_f32_16x16x32_bf16 v[112:115], v[152:155], v[160:163], 0
	v_mfma_f32_16x16x32_bf16 v[100:103], v[144:147], v[168:171], 0
	v_mfma_f32_16x16x32_bf16 v[96:99], v[152:155], v[168:171], 0
	v_mfma_f32_16x16x32_bf16 v[84:87], v[144:147], v[196:199], 0
	v_mfma_f32_16x16x32_bf16 v[80:83], v[152:155], v[196:199], 0
	v_mfma_f32_16x16x32_bf16 v[68:71], v[144:147], v[206:209], 0
	v_mfma_f32_16x16x32_bf16 v[64:67], v[152:155], v[206:209], 0
	v_mfma_f32_16x16x32_bf16 v[116:119], v[148:151], v[164:167], v[116:119]
	v_mfma_f32_16x16x32_bf16 v[112:115], v[156:159], v[164:167], v[112:115]
	v_mfma_f32_16x16x32_bf16 v[100:103], v[148:151], v[172:175], v[100:103]
	v_mfma_f32_16x16x32_bf16 v[96:99], v[156:159], v[172:175], v[96:99]
	v_mfma_f32_16x16x32_bf16 v[84:87], v[148:151], v[202:205], v[84:87]
	v_mfma_f32_16x16x32_bf16 v[80:83], v[156:159], v[202:205], v[80:83]
	v_mfma_f32_16x16x32_bf16 v[68:71], v[148:151], v[232:235], v[68:71]
	v_mfma_f32_16x16x32_bf16 v[64:67], v[156:159], v[232:235], v[64:67]
	s_barrier
	s_setprio 0
	s_add_i32 s72, s48, s26
	v_lshl_add_u64 v[222:223], s[14:15], 0, v[182:183]
	s_mov_b32 m0, s72
	ds_read_b128 v[160:163], v220 offset:16384
	ds_read_b128 v[164:167], v220 offset:17408
	ds_read_b128 v[168:171], v220 offset:18432
	ds_read_b128 v[172:175], v220 offset:19456
	ds_read_b128 v[196:199], v220 offset:20480
	ds_read_b128 v[202:205], v220 offset:21504
	ds_read_b128 v[206:209], v220 offset:22528
	ds_read_b128 v[232:235], v220 offset:23552
	global_load_lds_dwordx4 v[222:223], off
	s_add_i32 m0, s72, 0x2000
	s_add_u32 s72, s14, 0x80000
	v_lshl_add_u64 v[228:229], s[14:15], 0, v[186:187]
	s_addc_u32 s73, s15, 0
	s_add_i32 s74, s49, s26
	global_load_lds_dwordx4 v[228:229], off
	v_lshl_add_u64 v[236:237], s[72:73], 0, v[182:183]
	s_mov_b32 m0, s74
	v_lshl_add_u64 v[238:239], s[16:17], 0, v[184:185]
	global_load_lds_dwordx4 v[236:237], off
	v_lshl_add_u64 v[236:237], s[72:73], 0, v[186:187]
	s_add_i32 m0, s74, 0x2000
	s_nop 0
	global_load_lds_dwordx4 v[236:237], off
	v_lshl_add_u64 v[236:237], s[16:17], 0, v[180:181]
	s_mov_b32 m0, s27
	s_nop 0
	global_load_lds_dwordx4 v[236:237], off
	s_mov_b32 m0, s28
	s_nop 0
	global_load_lds_dwordx4 v[238:239], off
	s_waitcnt vmcnt(8)
	s_waitcnt lgkmcnt(0)
	s_setprio 1
	s_barrier
	v_mfma_f32_16x16x32_bf16 v[60:63], v[128:131], v[160:163], 0
	v_mfma_f32_16x16x32_bf16 v[56:59], v[136:139], v[160:163], 0
	v_mfma_f32_16x16x32_bf16 v[44:47], v[128:131], v[168:171], 0
	v_mfma_f32_16x16x32_bf16 v[40:43], v[136:139], v[168:171], 0
	v_mfma_f32_16x16x32_bf16 v[28:31], v[128:131], v[196:199], 0
	v_mfma_f32_16x16x32_bf16 v[24:27], v[136:139], v[196:199], 0
	v_mfma_f32_16x16x32_bf16 v[12:15], v[128:131], v[206:209], 0
	v_mfma_f32_16x16x32_bf16 v[8:11], v[136:139], v[206:209], 0
	v_mfma_f32_16x16x32_bf16 v[60:63], v[132:135], v[164:167], v[60:63]
	v_mfma_f32_16x16x32_bf16 v[56:59], v[140:143], v[164:167], v[56:59]
	v_mfma_f32_16x16x32_bf16 v[44:47], v[132:135], v[172:175], v[44:47]
	v_mfma_f32_16x16x32_bf16 v[40:43], v[140:143], v[172:175], v[40:43]
	v_mfma_f32_16x16x32_bf16 v[28:31], v[132:135], v[202:205], v[28:31]
	v_mfma_f32_16x16x32_bf16 v[24:27], v[140:143], v[202:205], v[24:27]
	v_mfma_f32_16x16x32_bf16 v[12:15], v[132:135], v[232:235], v[12:15]
	v_mfma_f32_16x16x32_bf16 v[8:11], v[140:143], v[232:235], v[8:11]
	s_setprio 0
	s_setprio 1
	v_mfma_f32_16x16x32_bf16 v[52:55], v[144:147], v[160:163], 0
	v_mfma_f32_16x16x32_bf16 v[48:51], v[152:155], v[160:163], 0
	v_mfma_f32_16x16x32_bf16 v[36:39], v[144:147], v[168:171], 0
	v_mfma_f32_16x16x32_bf16 v[32:35], v[152:155], v[168:171], 0
	v_mfma_f32_16x16x32_bf16 v[20:23], v[144:147], v[196:199], 0
	v_mfma_f32_16x16x32_bf16 v[16:19], v[152:155], v[196:199], 0
	v_mfma_f32_16x16x32_bf16 v[4:7], v[144:147], v[206:209], 0
	v_mfma_f32_16x16x32_bf16 v[0:3], v[152:155], v[206:209], 0
	v_mfma_f32_16x16x32_bf16 v[52:55], v[148:151], v[164:167], v[52:55]
	v_mfma_f32_16x16x32_bf16 v[48:51], v[156:159], v[164:167], v[48:51]
	v_mfma_f32_16x16x32_bf16 v[36:39], v[148:151], v[172:175], v[36:39]
	v_mfma_f32_16x16x32_bf16 v[32:35], v[156:159], v[172:175], v[32:35]
	v_mfma_f32_16x16x32_bf16 v[20:23], v[148:151], v[202:205], v[20:23]
	v_mfma_f32_16x16x32_bf16 v[16:19], v[156:159], v[202:205], v[16:19]
	v_mfma_f32_16x16x32_bf16 v[4:7], v[148:151], v[232:235], v[4:7]
	v_mfma_f32_16x16x32_bf16 v[0:3], v[156:159], v[232:235], v[0:3]
	s_barrier
; #define PG8_STAGE(bufoff, gbase, voff) do { _Pragma("unroll") for (int _i = 0; _i < 2; ++_i) \
;         __builtin_amdgcn_global_load_lds((const unsigned*)((const char*)(gbase) + (voff)[_i]), (PG8_LAS unsigned*)(lds + (bufoff) + ldsw + _i * 8192), 16, 0, 0); } while (0)
; #define PG8_LDA(dst, b, h) do { _Pragma("unroll") for (int m = 0; m < 4; ++m) _Pragma("unroll") for (int k = 0; k < 2; ++k) dst[m][k] = *(const PG8_LAS bf16x8*)(lds + PG8_SA(b, h) + aoff + m * 2048 + k * 1024); } while (0)
; #define PG8_LDB(dst, b, h) do { _Pragma("unroll") for (int n = 0; n < 2; ++n) _Pragma("unroll") for (int k = 0; k < 2; ++k) dst[n][k] = *(const PG8_LAS bf16x8*)(lds + PG8_SB(b, h) + boff + n * 2048 + k * 1024); } while (0)
; #define PG8_MMA(ai, bj, At, Bt) do { __builtin_amdgcn_s_setprio(1); _Pragma("unroll") for (int m = 0; m < 4; ++m) _Pragma("unroll") for (int n = 0; n < 2; ++n) _Pragma("unroll") for (int k = 0; k < 2; ++k) \
;         acc[ai][bj][m][n] = __builtin_amdgcn_mfma_f32_16x16x32_bf16(Bt[n][k], At[m][k], acc[ai][bj][m][n], 0, 0, 0); __builtin_amdgcn_s_setprio(0); } while (0)
; #define PG8_WAIT_V(n) asm volatile("s_waitcnt vmcnt(" #n ")" ::: "memory")
; #define PG8_WAIT_L(n) asm volatile("s_waitcnt lgkmcnt(" #n ")" ::: "memory")
; #define PG8_BAR __builtin_amdgcn_s_barrier()
; #define PG8_SCHED __builtin_amdgcn_sched_barrier(0)
; template <class Epi, class Sched, bool ALIGN_EPI = false, bool SP2 = false, bool DUAL = false>
; __device__ __forceinline__ void gemm_phase(PG8_LAS unsigned char* lds, const Gemm g, const Sched& S, const Epi& E) {
;     ...
;             PG8_LDB(B0, 1, 0); PG8_LDB(B1, 1, 1); PG8_SCHED; PG8_LDA(At, 1, 0); PG8_STAGE(PG8_SA(0, 1), a2 + hstep, voffA);
;             PG8_WAIT_V(8); PG8_WAIT_L(0); PG8_BAR; PG8_MMA(0, 0, At, B0); PG8_MMA(0, 1, At, B1); PG8_BAR; PG8_SCHED;
	s_setprio 0
	s_add_i32 s72, 0, 0x18000
	s_add_i32 s73, 0, 0x1c000
	v_add_u32_e32 v140, s72, v216
	v_add_u32_e32 v156, s73, v216
	ds_read_b128 v[128:131], v140
	ds_read_b128 v[132:135], v140 offset:1024
	ds_read_b128 v[136:139], v140 offset:2048
	ds_read_b128 v[140:143], v140 offset:3072
	ds_read_b128 v[144:147], v156
	ds_read_b128 v[148:151], v156 offset:1024
	ds_read_b128 v[152:155], v156 offset:2048
	ds_read_b128 v[156:159], v156 offset:3072
	s_add_u32 s16, s16, 0x80000
	s_addc_u32 s17, s17, 0
	s_mov_b32 m0, s29
	v_lshl_add_u64 v[240:241], s[16:17], 0, v[180:181]
	ds_read_b128 v[160:163], v220 offset:32768
	ds_read_b128 v[164:167], v220 offset:33792
	ds_read_b128 v[168:171], v220 offset:34816
	ds_read_b128 v[172:175], v220 offset:35840
	ds_read_b128 v[196:199], v220 offset:36864
	ds_read_b128 v[202:205], v220 offset:37888
	ds_read_b128 v[206:209], v220 offset:38912
	ds_read_b128 v[232:235], v220 offset:39936
	global_load_lds_dwordx4 v[240:241], off
	v_lshl_add_u64 v[240:241], s[16:17], 0, v[184:185]
	s_mov_b32 m0, s34
	s_nop 0
	global_load_lds_dwordx4 v[240:241], off
	s_waitcnt vmcnt(8)
	s_waitcnt lgkmcnt(0)
	s_setprio 1
	s_barrier
	v_mfma_f32_16x16x32_bf16 v[124:127], v[128:131], v[160:163], v[124:127]
	v_mfma_f32_16x16x32_bf16 v[120:123], v[136:139], v[160:163], v[120:123]
	v_mfma_f32_16x16x32_bf16 v[108:111], v[128:131], v[168:171], v[108:111]
	v_mfma_f32_16x16x32_bf16 v[104:107], v[136:139], v[168:171], v[104:107]
	v_mfma_f32_16x16x32_bf16 v[92:95], v[128:131], v[196:199], v[92:95]
	v_mfma_f32_16x16x32_bf16 v[88:91], v[136:139], v[196:199], v[88:91]
	v_mfma_f32_16x16x32_bf16 v[76:79], v[128:131], v[206:209], v[76:79]
	v_mfma_f32_16x16x32_bf16 v[72:75], v[136:139], v[206:209], v[72:75]
	v_mfma_f32_16x16x32_bf16 v[124:127], v[132:135], v[164:167], v[124:127]
	v_mfma_f32_16x16x32_bf16 v[120:123], v[140:143], v[164:167], v[120:123]
	v_mfma_f32_16x16x32_bf16 v[108:111], v[132:135], v[172:175], v[108:111]
	v_mfma_f32_16x16x32_bf16 v[104:107], v[140:143], v[172:175], v[104:107]
	v_mfma_f32_16x16x32_bf16 v[92:95], v[132:135], v[202:205], v[92:95]
	v_mfma_f32_16x16x32_bf16 v[88:91], v[140:143], v[202:205], v[88:91]
	v_mfma_f32_16x16x32_bf16 v[76:79], v[132:135], v[232:235], v[76:79]
	v_mfma_f32_16x16x32_bf16 v[72:75], v[140:143], v[232:235], v[72:75]
	s_setprio 0
	s_setprio 1
	v_mfma_f32_16x16x32_bf16 v[116:119], v[144:147], v[160:163], v[116:119]
	v_mfma_f32_16x16x32_bf16 v[112:115], v[152:155], v[160:163], v[112:115]
	v_mfma_f32_16x16x32_bf16 v[100:103], v[144:147], v[168:171], v[100:103]
	v_mfma_f32_16x16x32_bf16 v[96:99], v[152:155], v[168:171], v[96:99]
	v_mfma_f32_16x16x32_bf16 v[84:87], v[144:147], v[196:199], v[84:87]
	v_mfma_f32_16x16x32_bf16 v[80:83], v[152:155], v[196:199], v[80:83]
	v_mfma_f32_16x16x32_bf16 v[68:71], v[144:147], v[206:209], v[68:71]
	v_mfma_f32_16x16x32_bf16 v[64:67], v[152:155], v[206:209], v[64:67]
	v_mfma_f32_16x16x32_bf16 v[116:119], v[148:151], v[164:167], v[116:119]
	v_mfma_f32_16x16x32_bf16 v[112:115], v[156:159], v[164:167], v[112:115]
	v_mfma_f32_16x16x32_bf16 v[100:103], v[148:151], v[172:175], v[100:103]
	v_mfma_f32_16x16x32_bf16 v[96:99], v[156:159], v[172:175], v[96:99]
	v_mfma_f32_16x16x32_bf16 v[84:87], v[148:151], v[202:205], v[84:87]
	v_mfma_f32_16x16x32_bf16 v[80:83], v[156:159], v[202:205], v[80:83]
	v_mfma_f32_16x16x32_bf16 v[68:71], v[148:151], v[232:235], v[68:71]
	v_mfma_f32_16x16x32_bf16 v[64:67], v[156:159], v[232:235], v[64:67]
	s_barrier
; #define PG8_STAGE(bufoff, gbase, voff) do { _Pragma("unroll") for (int _i = 0; _i < 2; ++_i) \
;         __builtin_amdgcn_global_load_lds((const unsigned*)((const char*)(gbase) + (voff)[_i]), (PG8_LAS unsigned*)(lds + (bufoff) + ldsw + _i * 8192), 16, 0, 0); } while (0)
; #define PG8_LDA(dst, b, h) do { _Pragma("unroll") for (int m = 0; m < 4; ++m) _Pragma("unroll") for (int k = 0; k < 2; ++k) dst[m][k] = *(const PG8_LAS bf16x8*)(lds + PG8_SA(b, h) + aoff + m * 2048 + k * 1024); } while (0)
; #define PG8_MMA(ai, bj, At, Bt) do { __builtin_amdgcn_s_setprio(1); _Pragma("unroll") for (int m = 0; m < 4; ++m) _Pragma("unroll") for (int n = 0; n < 2; ++n) _Pragma("unroll") for (int k = 0; k < 2; ++k) \
;         acc[ai][bj][m][n] = __builtin_amdgcn_mfma_f32_16x16x32_bf16(Bt[n][k], At[m][k], acc[ai][bj][m][n], 0, 0, 0); __builtin_amdgcn_s_setprio(0); } while (0)
; #define PG8_WAIT_V(n) asm volatile("s_waitcnt vmcnt(" #n ")" ::: "memory")
; #define PG8_WAIT_L(n) asm volatile("s_waitcnt lgkmcnt(" #n ")" ::: "memory")
; #define PG8_BAR __builtin_amdgcn_s_barrier()
; #define PG8_SCHED __builtin_amdgcn_sched_barrier(0)
; template <class Epi, class Sched, bool ALIGN_EPI = false, bool SP2 = false, bool DUAL = false>
; __device__ __forceinline__ void gemm_phase(PG8_LAS unsigned char* lds, const Gemm g, const Sched& S, const Epi& E) {
;     ...
;             PG8_LDA(At, 1, 1); PG8_STAGE(PG8_SB(1, 0), b3, voffB); PG8_STAGE(PG8_SB(1, 1), b3 + hstep, voffB); PG8_STAGE(PG8_SA(1, 0), a3, voffA);
;             PG8_WAIT_V(8); PG8_WAIT_L(0); PG8_BAR; PG8_MMA(1, 0, At, B0); PG8_MMA(1, 1, At, B1); PG8_BAR; PG8_SCHED;
	s_setprio 0
	s_add_i32 s16, s72, s26
	v_lshl_add_u64 v[222:223], v[222:223], 0, s[36:37]
	s_mov_b32 m0, s16
	ds_read_b128 v[160:163], v220 offset:49152
	ds_read_b128 v[164:167], v220 offset:50176
	ds_read_b128 v[168:171], v220 offset:51200
	ds_read_b128 v[172:175], v220 offset:52224
	ds_read_b128 v[196:199], v220 offset:53248
	ds_read_b128 v[202:205], v220 offset:54272
	ds_read_b128 v[206:209], v220 offset:55296
	ds_read_b128 v[232:235], v220 offset:56320
	global_load_lds_dwordx4 v[222:223], off
	s_add_i32 m0, s16, 0x2000
	s_add_u32 s14, s14, 0x80080
	v_lshl_add_u64 v[222:223], v[228:229], 0, s[36:37]
	s_addc_u32 s15, s15, 0
	s_add_i32 s16, s73, s26
	global_load_lds_dwordx4 v[222:223], off
	v_lshl_add_u64 v[222:223], s[14:15], 0, v[182:183]
	s_mov_b32 m0, s16
	s_nop 0
	global_load_lds_dwordx4 v[222:223], off
	v_lshl_add_u64 v[222:223], s[14:15], 0, v[186:187]
	s_add_i32 m0, s16, 0x2000
	s_nop 0
	global_load_lds_dwordx4 v[222:223], off
	v_lshl_add_u64 v[222:223], v[236:237], 0, s[36:37]
	s_mov_b32 m0, s44
	s_nop 0
	global_load_lds_dwordx4 v[222:223], off
	v_lshl_add_u64 v[222:223], v[238:239], 0, s[36:37]
	s_mov_b32 m0, s45
	s_nop 0
	global_load_lds_dwordx4 v[222:223], off
	s_waitcnt vmcnt(8)
	s_waitcnt lgkmcnt(0)
	s_setprio 1
	s_barrier
	v_mfma_f32_16x16x32_bf16 v[60:63], v[128:131], v[160:163], v[60:63]
	v_mfma_f32_16x16x32_bf16 v[56:59], v[136:139], v[160:163], v[56:59]
	v_mfma_f32_16x16x32_bf16 v[44:47], v[128:131], v[168:171], v[44:47]
	v_mfma_f32_16x16x32_bf16 v[40:43], v[136:139], v[168:171], v[40:43]
	v_mfma_f32_16x16x32_bf16 v[28:31], v[128:131], v[196:199], v[28:31]
	v_mfma_f32_16x16x32_bf16 v[24:27], v[136:139], v[196:199], v[24:27]
	v_mfma_f32_16x16x32_bf16 v[12:15], v[128:131], v[206:209], v[12:15]
	v_mfma_f32_16x16x32_bf16 v[8:11], v[136:139], v[206:209], v[8:11]
	v_mfma_f32_16x16x32_bf16 v[60:63], v[132:135], v[164:167], v[60:63]
	v_mfma_f32_16x16x32_bf16 v[56:59], v[140:143], v[164:167], v[56:59]
	v_mfma_f32_16x16x32_bf16 v[44:47], v[132:135], v[172:175], v[44:47]
	v_mfma_f32_16x16x32_bf16 v[40:43], v[140:143], v[172:175], v[40:43]
	v_mfma_f32_16x16x32_bf16 v[28:31], v[132:135], v[202:205], v[28:31]
	v_mfma_f32_16x16x32_bf16 v[24:27], v[140:143], v[202:205], v[24:27]
	v_mfma_f32_16x16x32_bf16 v[12:15], v[132:135], v[232:235], v[12:15]
	v_mfma_f32_16x16x32_bf16 v[8:11], v[140:143], v[232:235], v[8:11]
	s_setprio 0
	s_setprio 1
	v_mfma_f32_16x16x32_bf16 v[52:55], v[144:147], v[160:163], v[52:55]
	v_mfma_f32_16x16x32_bf16 v[48:51], v[152:155], v[160:163], v[48:51]
	v_mfma_f32_16x16x32_bf16 v[36:39], v[144:147], v[168:171], v[36:39]
	v_mfma_f32_16x16x32_bf16 v[32:35], v[152:155], v[168:171], v[32:35]
	v_mfma_f32_16x16x32_bf16 v[20:23], v[144:147], v[196:199], v[20:23]
	v_mfma_f32_16x16x32_bf16 v[16:19], v[152:155], v[196:199], v[16:19]
	v_mfma_f32_16x16x32_bf16 v[4:7], v[144:147], v[206:209], v[4:7]
	v_mfma_f32_16x16x32_bf16 v[0:3], v[152:155], v[206:209], v[0:3]
	v_mfma_f32_16x16x32_bf16 v[52:55], v[148:151], v[164:167], v[52:55]
	v_mfma_f32_16x16x32_bf16 v[48:51], v[156:159], v[164:167], v[48:51]
	v_mfma_f32_16x16x32_bf16 v[36:39], v[148:151], v[172:175], v[36:39]
	v_mfma_f32_16x16x32_bf16 v[32:35], v[156:159], v[172:175], v[32:35]
	v_mfma_f32_16x16x32_bf16 v[20:23], v[148:151], v[202:205], v[20:23]
	v_mfma_f32_16x16x32_bf16 v[16:19], v[156:159], v[202:205], v[16:19]
	v_mfma_f32_16x16x32_bf16 v[4:7], v[148:151], v[232:235], v[4:7]
	v_mfma_f32_16x16x32_bf16 v[0:3], v[156:159], v[232:235], v[0:3]
	s_barrier
	s_setprio 0
	s_add_i32 s71, s71, 2
	s_add_u32 s68, s68, 0x100
	s_addc_u32 s69, s69, 0
	s_add_u32 s67, s67, 0x100
	s_addc_u32 s70, s70, 0

;     __device__ bool next(int i, Unit& u) const { if (!base.next(i >> 1, u)) return false; u.sub = i & 1; return true; }
; #define PG8_STAGE(bufoff, gbase, voff) do { _Pragma("unroll") for (int _i = 0; _i < 2; ++_i) \
;         __builtin_amdgcn_global_load_lds((const unsigned*)((const char*)(gbase) + (voff)[_i]), (PG8_LAS unsigned*)(lds + (bufoff) + ldsw + _i * 8192), 16, 0, 0); } while (0)
; #define PG8_LDA(dst, b, h) do { _Pragma("unroll") for (int m = 0; m < 4; ++m) _Pragma("unroll") for (int k = 0; k < 2; ++k) dst[m][k] = *(const PG8_LAS bf16x8*)(lds + PG8_SA(b, h) + aoff + m * 2048 + k * 1024); } while (0)
; #define PG8_LDB(dst, b, h) do { _Pragma("unroll") for (int n = 0; n < 2; ++n) _Pragma("unroll") for (int k = 0; k < 2; ++k) dst[n][k] = *(const PG8_LAS bf16x8*)(lds + PG8_SB(b, h) + boff + n * 2048 + k * 1024); } while (0)
; #define PG8_SCHED __builtin_amdgcn_sched_barrier(0)
;     __host__ __device__ bool next(int i, Unit& u) const {
;         const long L = (long)i * G + c; if (L >= nwg) return false;
;         int wgid = (int)L; { const int q = nwg / NXCD, r = nwg % NXCD, xcd = wgid % NXCD, off = wgid / NXCD; wgid = (xcd < r ? xcd * (q + 1) : r * (q + 1) + (xcd - r) * q) + off; }
; template <class Epi, class Sched, bool ALIGN_EPI = false, bool SP2 = false, bool DUAL = false>
; __device__ __forceinline__ void gemm_phase(PG8_LAS unsigned char* lds, const Gemm g, const Sched& S, const Epi& E) {
;     ...
;         const bool has_next = S.next(ui + 1, nxt);
;     ...
;             PG8_LDB(B0, 0, 0); PG8_LDB(B1, 0, 1); PG8_SCHED; PG8_LDA(At, 0, 0); PG8_STAGE(PG8_SA(1, 1), a1 + hstep, voffA);
.LBB0_985:
	ds_read_b128 v[128:131], v215
	ds_read_b128 v[132:135], v215 offset:1024
	ds_read_b128 v[136:139], v215 offset:2048
	ds_read_b128 v[140:143], v215 offset:3072
	ds_read_b128 v[144:147], v216
	ds_read_b128 v[148:151], v216 offset:1024
	ds_read_b128 v[152:155], v216 offset:2048
	ds_read_b128 v[156:159], v216 offset:3072
	ds_read_b128 v[160:163], v217
	ds_read_b128 v[164:167], v217 offset:1024
	ds_read_b128 v[188:191], v217 offset:2048
	ds_read_b128 v[192:195], v217 offset:3072
	ds_read_b128 v[196:199], v217 offset:4096
	ds_read_b128 v[202:205], v217 offset:5120
	ds_read_b128 v[206:209], v217 offset:6144
	ds_read_b128 v[220:223], v217 offset:7168
	s_add_i32 s45, s45, 1
	s_mul_i32 s4, s45, s46
	s_mul_hi_u32 s5, s45, s49
	s_add_i32 s5, s5, s4
	s_mul_i32 s4, s45, s49
	s_add_u32 s28, s4, s2
	s_addc_u32 s29, s5, s35
	v_cmp_gt_i64_e32 vcc, s[28:29], v[186:187]
	v_cmp_lt_i64_e64 s[4:5], s[28:29], v[184:185]
	s_cbranch_vccnz .LBB0_991
	s_ashr_i32 s22, s28, 31
	s_lshr_b32 s22, s22, 29
	s_add_i32 s24, s28, s22
	s_and_b32 s22, s24, -8
	s_sub_i32 s25, s28, s22
	s_cmp_gt_i32 s25, 3
	s_mov_b64 s[22:23], -1
	s_cbranch_scc0 .LBB0_988
	s_mul_i32 s22, s25, 0x2c5
	s_add_i32 s28, s22, 4
	s_mov_b64 s[22:23], 0

; #define PG8_STAGE(bufoff, gbase, voff) do { _Pragma("unroll") for (int _i = 0; _i < 2; ++_i) \
;         __builtin_amdgcn_global_load_lds((const unsigned*)((const char*)(gbase) + (voff)[_i]), (PG8_LAS unsigned*)(lds + (bufoff) + ldsw + _i * 8192), 16, 0, 0); } while (0)
; #define PG8_LDA(dst, b, h) do { _Pragma("unroll") for (int m = 0; m < 4; ++m) _Pragma("unroll") for (int k = 0; k < 2; ++k) dst[m][k] = *(const PG8_LAS bf16x8*)(lds + PG8_SA(b, h) + aoff + m * 2048 + k * 1024); } while (0)
; #define PG8_LDB(dst, b, h) do { _Pragma("unroll") for (int n = 0; n < 2; ++n) _Pragma("unroll") for (int k = 0; k < 2; ++k) dst[n][k] = *(const PG8_LAS bf16x8*)(lds + PG8_SB(b, h) + boff + n * 2048 + k * 1024); } while (0)
; #define PG8_WAIT_V(n) asm volatile("s_waitcnt vmcnt(" #n ")" ::: "memory")
; #define PG8_WAIT_L(n) asm volatile("s_waitcnt lgkmcnt(" #n ")" ::: "memory")
; #define PG8_BAR __builtin_amdgcn_s_barrier()
; #define PG8_SCHED __builtin_amdgcn_sched_barrier(0)
; template <class Epi, class Sched, bool ALIGN_EPI = false, bool SP2 = false, bool DUAL = false>
; __device__ __forceinline__ void gemm_phase(PG8_LAS unsigned char* lds, const Gemm g, const Sched& S, const Epi& E) {
;     ...
;             const char* a2 = last ? nA : cA + (size_t)(t + 2) * kstep; const char* b2 = last ? nB : cB + (size_t)(t + 2) * kstep;
;             const char* a3 = a2 + kstep; const char* b3 = b2 + kstep;
;             if (last && has_next) S.a_ready(nxt);
;             if constexpr (SP2) {
;             PG8_LDB(B0, 0, 0); PG8_LDB(B1, 0, 1); PG8_SCHED; PG8_LDA(At, 0, 0); PG8_STAGE(PG8_SA(1, 1), a1 + hstep, voffA);
;             PG8_WAIT_V(8); PG8_WAIT_L(0); PG8_BAR; PG8_MMA(0, 0, At, B0); PG8_MMA(0, 1, At, B1); PG8_BAR; PG8_SCHED;
;             PG8_LDA(At, 0, 1); PG8_STAGE(PG8_SB(0, 0), b2, voffB); PG8_STAGE(PG8_SB(0, 1), b2 + hstep, voffB); PG8_STAGE(PG8_SA(0, 0), a2, voffA);
;             PG8_WAIT_V(8); PG8_WAIT_L(0); PG8_BAR; PG8_MMA(1, 0, At, B0); PG8_MMA(1, 1, At, B1); PG8_BAR; PG8_SCHED;
;     ...
;         if (!keep)
; #pragma unroll
;         for (int a = 0; a < 2; ++a)
; #pragma unroll
;             for (int b = 0; b < 2; ++b)
; #pragma unroll
;                 for (int m = 0; m < 4; ++m)
; #pragma unroll
;                     for (int n = 0; n < 2; ++n) acc[a][b][m][n] = (f32x4){0.f, 0.f, 0.f, 0.f};
.LBB0_991:
	s_ashr_i32 s25, s24, 31
	s_lshl_b64 s[28:29], s[24:25], 20
	s_add_u32 s30, s19, s28
	s_addc_u32 s31, s21, s29
	s_and_b64 s[28:29], s[4:5], exec
	s_cselect_b32 s25, s31, s27
	s_cselect_b32 s28, s30, s26
	s_ashr_i32 s23, s22, 31
	s_lshl_b64 s[36:37], s[22:23], 20
	s_add_u32 s36, s8, s36
	s_addc_u32 s37, s9, s37
	s_and_b64 s[40:41], s[4:5], exec
	s_cselect_b32 s23, s37, s15
	s_cselect_b32 s29, s36, s14
	s_add_u32 s40, s26, 0x80080
	s_addc_u32 s41, s27, 0
	s_add_u32 s63, s14, 0x100
	s_addc_u32 s64, s15, 0
	s_mov_b32 s65, -2
	s_add_u32 s14, s40, 0xfff80080
	s_addc_u32 s15, s41, -1
	s_cmp_eq_u32 s65, 28
	s_cselect_b32 s27, s25, s15
	s_cselect_b32 s26, s28, s14
	s_cselect_b32 s15, s23, s64
	s_cselect_b32 s14, s29, s63
	v_lshl_add_u64 v[228:229], s[40:41], 0, v[180:181]
	s_add_i32 m0, s39, 0xc000
	s_nop 0
	global_load_lds_dwordx4 v[228:229], off
	v_lshl_add_u64 v[228:229], s[40:41], 0, v[182:183]
	s_add_i32 m0, s39, 0xe000
	s_nop 0
	global_load_lds_dwordx4 v[228:229], off
	s_waitcnt vmcnt(8)
	s_waitcnt lgkmcnt(0)
	s_setprio 1
	s_barrier
	v_mfma_f32_16x16x32_bf16 v[124:127], v[128:131], v[160:163], 0
	v_mfma_f32_16x16x32_bf16 v[120:123], v[136:139], v[160:163], 0
	v_mfma_f32_16x16x32_bf16 v[108:111], v[128:131], v[188:191], 0
	v_mfma_f32_16x16x32_bf16 v[104:107], v[136:139], v[188:191], 0
	v_mfma_f32_16x16x32_bf16 v[92:95], v[128:131], v[196:199], 0
	v_mfma_f32_16x16x32_bf16 v[88:91], v[136:139], v[196:199], 0
	v_mfma_f32_16x16x32_bf16 v[76:79], v[128:131], v[206:209], 0
	v_mfma_f32_16x16x32_bf16 v[72:75], v[136:139], v[206:209], 0
	v_mfma_f32_16x16x32_bf16 v[124:127], v[132:135], v[164:167], v[124:127]
	v_mfma_f32_16x16x32_bf16 v[120:123], v[140:143], v[164:167], v[120:123]
	v_mfma_f32_16x16x32_bf16 v[108:111], v[132:135], v[192:195], v[108:111]
	v_mfma_f32_16x16x32_bf16 v[104:107], v[140:143], v[192:195], v[104:107]
	v_mfma_f32_16x16x32_bf16 v[92:95], v[132:135], v[202:205], v[92:95]
	v_mfma_f32_16x16x32_bf16 v[88:91], v[140:143], v[202:205], v[88:91]
	v_mfma_f32_16x16x32_bf16 v[76:79], v[132:135], v[220:223], v[76:79]
	v_mfma_f32_16x16x32_bf16 v[72:75], v[140:143], v[220:223], v[72:75]
	s_setprio 0
	s_setprio 1
	v_mfma_f32_16x16x32_bf16 v[116:119], v[144:147], v[160:163], 0
	v_mfma_f32_16x16x32_bf16 v[112:115], v[152:155], v[160:163], 0
	v_mfma_f32_16x16x32_bf16 v[100:103], v[144:147], v[188:191], 0
	v_mfma_f32_16x16x32_bf16 v[96:99], v[152:155], v[188:191], 0
	v_mfma_f32_16x16x32_bf16 v[84:87], v[144:147], v[196:199], 0
	v_mfma_f32_16x16x32_bf16 v[80:83], v[152:155], v[196:199], 0
	v_mfma_f32_16x16x32_bf16 v[68:71], v[144:147], v[206:209], 0
	v_mfma_f32_16x16x32_bf16 v[64:67], v[152:155], v[206:209], 0
	v_mfma_f32_16x16x32_bf16 v[116:119], v[148:151], v[164:167], v[116:119]
	v_mfma_f32_16x16x32_bf16 v[112:115], v[156:159], v[164:167], v[112:115]
	v_mfma_f32_16x16x32_bf16 v[100:103], v[148:151], v[192:195], v[100:103]
	v_mfma_f32_16x16x32_bf16 v[96:99], v[156:159], v[192:195], v[96:99]
	v_mfma_f32_16x16x32_bf16 v[84:87], v[148:151], v[202:205], v[84:87]
	v_mfma_f32_16x16x32_bf16 v[80:83], v[156:159], v[202:205], v[80:83]
	v_mfma_f32_16x16x32_bf16 v[68:71], v[148:151], v[220:223], v[68:71]
	v_mfma_f32_16x16x32_bf16 v[64:67], v[156:159], v[220:223], v[64:67]
	s_barrier
	s_setprio 0
	s_add_i32 s66, s50, s34
	v_lshl_add_u64 v[228:229], s[14:15], 0, v[170:171]
	s_mov_b32 m0, s66
	ds_read_b128 v[160:163], v217 offset:16384
	ds_read_b128 v[164:167], v217 offset:17408
	ds_read_b128 v[188:191], v217 offset:18432
	ds_read_b128 v[192:195], v217 offset:19456
	ds_read_b128 v[196:199], v217 offset:20480
	ds_read_b128 v[202:205], v217 offset:21504
	ds_read_b128 v[206:209], v217 offset:22528
	ds_read_b128 v[220:223], v217 offset:23552
	global_load_lds_dwordx4 v[228:229], off
	s_add_i32 m0, s66, 0x2000
	s_add_u32 s66, s14, 0x80000
	v_lshl_add_u64 v[232:233], s[14:15], 0, v[174:175]
	s_addc_u32 s67, s15, 0
	s_add_i32 s68, s51, s34
	global_load_lds_dwordx4 v[232:233], off
	v_lshl_add_u64 v[234:235], s[66:67], 0, v[170:171]
	s_mov_b32 m0, s68
	v_lshl_add_u64 v[236:237], s[26:27], 0, v[172:173]
	global_load_lds_dwordx4 v[234:235], off
	v_lshl_add_u64 v[234:235], s[66:67], 0, v[174:175]
	s_add_i32 m0, s68, 0x2000
	s_nop 0
	global_load_lds_dwordx4 v[234:235], off
	v_lshl_add_u64 v[234:235], s[26:27], 0, v[168:169]
	s_mov_b32 m0, s39
	s_nop 0
	global_load_lds_dwordx4 v[234:235], off
	s_mov_b32 m0, s42
	s_nop 0
	global_load_lds_dwordx4 v[236:237], off
	s_waitcnt vmcnt(8)
	s_waitcnt lgkmcnt(0)
	s_setprio 1
	s_barrier
	v_mfma_f32_16x16x32_bf16 v[60:63], v[128:131], v[160:163], 0
	v_mfma_f32_16x16x32_bf16 v[56:59], v[136:139], v[160:163], 0
	v_mfma_f32_16x16x32_bf16 v[44:47], v[128:131], v[188:191], 0
	v_mfma_f32_16x16x32_bf16 v[40:43], v[136:139], v[188:191], 0
	v_mfma_f32_16x16x32_bf16 v[28:31], v[128:131], v[196:199], 0
	v_mfma_f32_16x16x32_bf16 v[24:27], v[136:139], v[196:199], 0
	v_mfma_f32_16x16x32_bf16 v[12:15], v[128:131], v[206:209], 0
	v_mfma_f32_16x16x32_bf16 v[8:11], v[136:139], v[206:209], 0
	v_mfma_f32_16x16x32_bf16 v[60:63], v[132:135], v[164:167], v[60:63]
	v_mfma_f32_16x16x32_bf16 v[56:59], v[140:143], v[164:167], v[56:59]
	v_mfma_f32_16x16x32_bf16 v[44:47], v[132:135], v[192:195], v[44:47]
	v_mfma_f32_16x16x32_bf16 v[40:43], v[140:143], v[192:195], v[40:43]
	v_mfma_f32_16x16x32_bf16 v[28:31], v[132:135], v[202:205], v[28:31]
	v_mfma_f32_16x16x32_bf16 v[24:27], v[140:143], v[202:205], v[24:27]
	v_mfma_f32_16x16x32_bf16 v[12:15], v[132:135], v[220:223], v[12:15]
	v_mfma_f32_16x16x32_bf16 v[8:11], v[140:143], v[220:223], v[8:11]
	s_setprio 0
	s_setprio 1
	v_mfma_f32_16x16x32_bf16 v[52:55], v[144:147], v[160:163], 0
	v_mfma_f32_16x16x32_bf16 v[48:51], v[152:155], v[160:163], 0
	v_mfma_f32_16x16x32_bf16 v[36:39], v[144:147], v[188:191], 0
	v_mfma_f32_16x16x32_bf16 v[32:35], v[152:155], v[188:191], 0
	v_mfma_f32_16x16x32_bf16 v[20:23], v[144:147], v[196:199], 0
	v_mfma_f32_16x16x32_bf16 v[16:19], v[152:155], v[196:199], 0
	v_mfma_f32_16x16x32_bf16 v[4:7], v[144:147], v[206:209], 0
	v_mfma_f32_16x16x32_bf16 v[0:3], v[152:155], v[206:209], 0
	v_mfma_f32_16x16x32_bf16 v[52:55], v[148:151], v[164:167], v[52:55]
	v_mfma_f32_16x16x32_bf16 v[48:51], v[156:159], v[164:167], v[48:51]
	v_mfma_f32_16x16x32_bf16 v[36:39], v[148:151], v[192:195], v[36:39]
	v_mfma_f32_16x16x32_bf16 v[32:35], v[156:159], v[192:195], v[32:35]
	v_mfma_f32_16x16x32_bf16 v[20:23], v[148:151], v[202:205], v[20:23]
	v_mfma_f32_16x16x32_bf16 v[16:19], v[156:159], v[202:205], v[16:19]
	v_mfma_f32_16x16x32_bf16 v[4:7], v[148:151], v[220:223], v[4:7]
	v_mfma_f32_16x16x32_bf16 v[0:3], v[156:159], v[220:223], v[0:3]
	s_barrier
; #define PG8_STAGE(bufoff, gbase, voff) do { _Pragma("unroll") for (int _i = 0; _i < 2; ++_i) \
;         __builtin_amdgcn_global_load_lds((const unsigned*)((const char*)(gbase) + (voff)[_i]), (PG8_LAS unsigned*)(lds + (bufoff) + ldsw + _i * 8192), 16, 0, 0); } while (0)
; #define PG8_LDA(dst, b, h) do { _Pragma("unroll") for (int m = 0; m < 4; ++m) _Pragma("unroll") for (int k = 0; k < 2; ++k) dst[m][k] = *(const PG8_LAS bf16x8*)(lds + PG8_SA(b, h) + aoff + m * 2048 + k * 1024); } while (0)
; #define PG8_LDB(dst, b, h) do { _Pragma("unroll") for (int n = 0; n < 2; ++n) _Pragma("unroll") for (int k = 0; k < 2; ++k) dst[n][k] = *(const PG8_LAS bf16x8*)(lds + PG8_SB(b, h) + boff + n * 2048 + k * 1024); } while (0)
; #define PG8_MMA(ai, bj, At, Bt) do { __builtin_amdgcn_s_setprio(1); _Pragma("unroll") for (int m = 0; m < 4; ++m) _Pragma("unroll") for (int n = 0; n < 2; ++n) _Pragma("unroll") for (int k = 0; k < 2; ++k) \
;         acc[ai][bj][m][n] = __builtin_amdgcn_mfma_f32_16x16x32_bf16(Bt[n][k], At[m][k], acc[ai][bj][m][n], 0, 0, 0); __builtin_amdgcn_s_setprio(0); } while (0)
; #define PG8_WAIT_V(n) asm volatile("s_waitcnt vmcnt(" #n ")" ::: "memory")
; #define PG8_WAIT_L(n) asm volatile("s_waitcnt lgkmcnt(" #n ")" ::: "memory")
; #define PG8_BAR __builtin_amdgcn_s_barrier()
; #define PG8_SCHED __builtin_amdgcn_sched_barrier(0)
; template <class Epi, class Sched, bool ALIGN_EPI = false, bool SP2 = false, bool DUAL = false>
; __device__ __forceinline__ void gemm_phase(PG8_LAS unsigned char* lds, const Gemm g, const Sched& S, const Epi& E) {
;     ...
;             PG8_LDB(B0, 1, 0); PG8_LDB(B1, 1, 1); PG8_SCHED; PG8_LDA(At, 1, 0); PG8_STAGE(PG8_SA(0, 1), a2 + hstep, voffA);
;             PG8_WAIT_V(8); PG8_WAIT_L(0); PG8_BAR; PG8_MMA(0, 0, At, B0); PG8_MMA(0, 1, At, B1); PG8_BAR; PG8_SCHED;
	s_setprio 0
	s_add_i32 s66, 0, 0x18000
	s_add_i32 s67, 0, 0x1c000
	v_add_u32_e32 v140, s66, v213
	v_add_u32_e32 v156, s67, v213
	ds_read_b128 v[128:131], v140
	ds_read_b128 v[132:135], v140 offset:1024
	ds_read_b128 v[136:139], v140 offset:2048
	ds_read_b128 v[140:143], v140 offset:3072
	ds_read_b128 v[144:147], v156
	ds_read_b128 v[148:151], v156 offset:1024
	ds_read_b128 v[152:155], v156 offset:2048
	ds_read_b128 v[156:159], v156 offset:3072
	s_add_u32 s26, s26, 0x80000
	s_addc_u32 s27, s27, 0
	s_mov_b32 m0, s43
	v_lshl_add_u64 v[238:239], s[26:27], 0, v[168:169]
	ds_read_b128 v[160:163], v217 offset:32768
	ds_read_b128 v[164:167], v217 offset:33792
	ds_read_b128 v[188:191], v217 offset:34816
	ds_read_b128 v[192:195], v217 offset:35840
	ds_read_b128 v[196:199], v217 offset:36864
	ds_read_b128 v[202:205], v217 offset:37888
	ds_read_b128 v[206:209], v217 offset:38912
	ds_read_b128 v[220:223], v217 offset:39936
	global_load_lds_dwordx4 v[238:239], off
	v_lshl_add_u64 v[238:239], s[26:27], 0, v[172:173]
	s_mov_b32 m0, s44
	s_nop 0
	global_load_lds_dwordx4 v[238:239], off
	s_waitcnt vmcnt(8)
	s_waitcnt lgkmcnt(0)
	s_setprio 1
	s_barrier
	v_mfma_f32_16x16x32_bf16 v[124:127], v[128:131], v[160:163], v[124:127]
	v_mfma_f32_16x16x32_bf16 v[120:123], v[136:139], v[160:163], v[120:123]
	v_mfma_f32_16x16x32_bf16 v[108:111], v[128:131], v[188:191], v[108:111]
	v_mfma_f32_16x16x32_bf16 v[104:107], v[136:139], v[188:191], v[104:107]
	v_mfma_f32_16x16x32_bf16 v[92:95], v[128:131], v[196:199], v[92:95]
	v_mfma_f32_16x16x32_bf16 v[88:91], v[136:139], v[196:199], v[88:91]
	v_mfma_f32_16x16x32_bf16 v[76:79], v[128:131], v[206:209], v[76:79]
	v_mfma_f32_16x16x32_bf16 v[72:75], v[136:139], v[206:209], v[72:75]
	v_mfma_f32_16x16x32_bf16 v[124:127], v[132:135], v[164:167], v[124:127]
	v_mfma_f32_16x16x32_bf16 v[120:123], v[140:143], v[164:167], v[120:123]
	v_mfma_f32_16x16x32_bf16 v[108:111], v[132:135], v[192:195], v[108:111]
	v_mfma_f32_16x16x32_bf16 v[104:107], v[140:143], v[192:195], v[104:107]
	v_mfma_f32_16x16x32_bf16 v[92:95], v[132:135], v[202:205], v[92:95]
	v_mfma_f32_16x16x32_bf16 v[88:91], v[140:143], v[202:205], v[88:91]
	v_mfma_f32_16x16x32_bf16 v[76:79], v[132:135], v[220:223], v[76:79]
	v_mfma_f32_16x16x32_bf16 v[72:75], v[140:143], v[220:223], v[72:75]
	s_setprio 0
	s_setprio 1
	v_mfma_f32_16x16x32_bf16 v[116:119], v[144:147], v[160:163], v[116:119]
	v_mfma_f32_16x16x32_bf16 v[112:115], v[152:155], v[160:163], v[112:115]
	v_mfma_f32_16x16x32_bf16 v[100:103], v[144:147], v[188:191], v[100:103]
	v_mfma_f32_16x16x32_bf16 v[96:99], v[152:155], v[188:191], v[96:99]
	v_mfma_f32_16x16x32_bf16 v[84:87], v[144:147], v[196:199], v[84:87]
	v_mfma_f32_16x16x32_bf16 v[80:83], v[152:155], v[196:199], v[80:83]
	v_mfma_f32_16x16x32_bf16 v[68:71], v[144:147], v[206:209], v[68:71]
	v_mfma_f32_16x16x32_bf16 v[64:67], v[152:155], v[206:209], v[64:67]
	v_mfma_f32_16x16x32_bf16 v[116:119], v[148:151], v[164:167], v[116:119]
	v_mfma_f32_16x16x32_bf16 v[112:115], v[156:159], v[164:167], v[112:115]
	v_mfma_f32_16x16x32_bf16 v[100:103], v[148:151], v[192:195], v[100:103]
	v_mfma_f32_16x16x32_bf16 v[96:99], v[156:159], v[192:195], v[96:99]
	v_mfma_f32_16x16x32_bf16 v[84:87], v[148:151], v[202:205], v[84:87]
	v_mfma_f32_16x16x32_bf16 v[80:83], v[156:159], v[202:205], v[80:83]
	v_mfma_f32_16x16x32_bf16 v[68:71], v[148:151], v[220:223], v[68:71]
	v_mfma_f32_16x16x32_bf16 v[64:67], v[156:159], v[220:223], v[64:67]
	s_barrier
; #define PG8_STAGE(bufoff, gbase, voff) do { _Pragma("unroll") for (int _i = 0; _i < 2; ++_i) \
;         __builtin_amdgcn_global_load_lds((const unsigned*)((const char*)(gbase) + (voff)[_i]), (PG8_LAS unsigned*)(lds + (bufoff) + ldsw + _i * 8192), 16, 0, 0); } while (0)
; #define PG8_LDA(dst, b, h) do { _Pragma("unroll") for (int m = 0; m < 4; ++m) _Pragma("unroll") for (int k = 0; k < 2; ++k) dst[m][k] = *(const PG8_LAS bf16x8*)(lds + PG8_SA(b, h) + aoff + m * 2048 + k * 1024); } while (0)
; #define PG8_MMA(ai, bj, At, Bt) do { __builtin_amdgcn_s_setprio(1); _Pragma("unroll") for (int m = 0; m < 4; ++m) _Pragma("unroll") for (int n = 0; n < 2; ++n) _Pragma("unroll") for (int k = 0; k < 2; ++k) \
;         acc[ai][bj][m][n] = __builtin_amdgcn_mfma_f32_16x16x32_bf16(Bt[n][k], At[m][k], acc[ai][bj][m][n], 0, 0, 0); __builtin_amdgcn_s_setprio(0); } while (0)
; #define PG8_WAIT_V(n) asm volatile("s_waitcnt vmcnt(" #n ")" ::: "memory")
; #define PG8_WAIT_L(n) asm volatile("s_waitcnt lgkmcnt(" #n ")" ::: "memory")
; #define PG8_BAR __builtin_amdgcn_s_barrier()
; #define PG8_SCHED __builtin_amdgcn_sched_barrier(0)
; template <class Epi, class Sched, bool ALIGN_EPI = false, bool SP2 = false, bool DUAL = false>
; __device__ __forceinline__ void gemm_phase(PG8_LAS unsigned char* lds, const Gemm g, const Sched& S, const Epi& E) {
;     ...
;             PG8_LDA(At, 1, 1); PG8_STAGE(PG8_SB(1, 0), b3, voffB); PG8_STAGE(PG8_SB(1, 1), b3 + hstep, voffB); PG8_STAGE(PG8_SA(1, 0), a3, voffA);
;             PG8_WAIT_V(8); PG8_WAIT_L(0); PG8_BAR; PG8_MMA(1, 0, At, B0); PG8_MMA(1, 1, At, B1); PG8_BAR; PG8_SCHED;
	s_setprio 0
	s_add_i32 s26, s66, s34
	v_lshl_add_u64 v[228:229], v[228:229], 0, s[12:13]
	s_mov_b32 m0, s26
	ds_read_b128 v[160:163], v217 offset:49152
	ds_read_b128 v[164:167], v217 offset:50176
	ds_read_b128 v[188:191], v217 offset:51200
	ds_read_b128 v[192:195], v217 offset:52224
	ds_read_b128 v[196:199], v217 offset:53248
	ds_read_b128 v[202:205], v217 offset:54272
	ds_read_b128 v[206:209], v217 offset:55296
	ds_read_b128 v[220:223], v217 offset:56320
	global_load_lds_dwordx4 v[228:229], off
	s_add_i32 m0, s26, 0x2000
	s_add_u32 s14, s14, 0x80080
	v_lshl_add_u64 v[228:229], v[232:233], 0, s[12:13]
	s_addc_u32 s15, s15, 0
	s_add_i32 s26, s67, s34
	global_load_lds_dwordx4 v[228:229], off
	v_lshl_add_u64 v[228:229], s[14:15], 0, v[170:171]
	s_mov_b32 m0, s26
	s_nop 0
	global_load_lds_dwordx4 v[228:229], off
	v_lshl_add_u64 v[228:229], s[14:15], 0, v[174:175]
	s_add_i32 m0, s26, 0x2000
	s_nop 0
	global_load_lds_dwordx4 v[228:229], off
	v_lshl_add_u64 v[228:229], v[234:235], 0, s[12:13]
	s_mov_b32 m0, s47
	s_nop 0
	global_load_lds_dwordx4 v[228:229], off
	v_lshl_add_u64 v[228:229], v[236:237], 0, s[12:13]
	s_mov_b32 m0, s48
	s_nop 0
	global_load_lds_dwordx4 v[228:229], off
	s_waitcnt vmcnt(8)
	s_waitcnt lgkmcnt(0)
	s_setprio 1
	s_barrier
	v_mfma_f32_16x16x32_bf16 v[60:63], v[128:131], v[160:163], v[60:63]
	v_mfma_f32_16x16x32_bf16 v[56:59], v[136:139], v[160:163], v[56:59]
	v_mfma_f32_16x16x32_bf16 v[44:47], v[128:131], v[188:191], v[44:47]
	v_mfma_f32_16x16x32_bf16 v[40:43], v[136:139], v[188:191], v[40:43]
	v_mfma_f32_16x16x32_bf16 v[28:31], v[128:131], v[196:199], v[28:31]
	v_mfma_f32_16x16x32_bf16 v[24:27], v[136:139], v[196:199], v[24:27]
	v_mfma_f32_16x16x32_bf16 v[12:15], v[128:131], v[206:209], v[12:15]
	v_mfma_f32_16x16x32_bf16 v[8:11], v[136:139], v[206:209], v[8:11]
	v_mfma_f32_16x16x32_bf16 v[60:63], v[132:135], v[164:167], v[60:63]
	v_mfma_f32_16x16x32_bf16 v[56:59], v[140:143], v[164:167], v[56:59]
	v_mfma_f32_16x16x32_bf16 v[44:47], v[132:135], v[192:195], v[44:47]
	v_mfma_f32_16x16x32_bf16 v[40:43], v[140:143], v[192:195], v[40:43]
	v_mfma_f32_16x16x32_bf16 v[28:31], v[132:135], v[202:205], v[28:31]
	v_mfma_f32_16x16x32_bf16 v[24:27], v[140:143], v[202:205], v[24:27]
	v_mfma_f32_16x16x32_bf16 v[12:15], v[132:135], v[220:223], v[12:15]
	v_mfma_f32_16x16x32_bf16 v[8:11], v[140:143], v[220:223], v[8:11]
	s_setprio 0
	s_setprio 1
	v_mfma_f32_16x16x32_bf16 v[52:55], v[144:147], v[160:163], v[52:55]
	v_mfma_f32_16x16x32_bf16 v[48:51], v[152:155], v[160:163], v[48:51]
	v_mfma_f32_16x16x32_bf16 v[36:39], v[144:147], v[188:191], v[36:39]
	v_mfma_f32_16x16x32_bf16 v[32:35], v[152:155], v[188:191], v[32:35]
	v_mfma_f32_16x16x32_bf16 v[20:23], v[144:147], v[196:199], v[20:23]
	v_mfma_f32_16x16x32_bf16 v[16:19], v[152:155], v[196:199], v[16:19]
	v_mfma_f32_16x16x32_bf16 v[4:7], v[144:147], v[206:209], v[4:7]
	v_mfma_f32_16x16x32_bf16 v[0:3], v[152:155], v[206:209], v[0:3]
	v_mfma_f32_16x16x32_bf16 v[52:55], v[148:151], v[164:167], v[52:55]
	v_mfma_f32_16x16x32_bf16 v[48:51], v[156:159], v[164:167], v[48:51]
	v_mfma_f32_16x16x32_bf16 v[36:39], v[148:151], v[192:195], v[36:39]
	v_mfma_f32_16x16x32_bf16 v[32:35], v[156:159], v[192:195], v[32:35]
	v_mfma_f32_16x16x32_bf16 v[20:23], v[148:151], v[202:205], v[20:23]
	v_mfma_f32_16x16x32_bf16 v[16:19], v[156:159], v[202:205], v[16:19]
	v_mfma_f32_16x16x32_bf16 v[4:7], v[148:151], v[220:223], v[4:7]
	v_mfma_f32_16x16x32_bf16 v[0:3], v[156:159], v[220:223], v[0:3]
	s_barrier
	s_setprio 0
	s_add_i32 s65, s65, 2
	s_add_u32 s40, s40, 0x100
	s_addc_u32 s41, s41, 0
	s_add_u32 s63, s63, 0x100
	s_addc_u32 s64, s64, 0

;     __device__ bool next(int i, Unit& u) const { if (!base.next(i >> 1, u)) return false; u.sub = i & 1; return true; }
; #define PG8_STAGE(bufoff, gbase, voff) do { _Pragma("unroll") for (int _i = 0; _i < 2; ++_i) \
;         __builtin_amdgcn_global_load_lds((const unsigned*)((const char*)(gbase) + (voff)[_i]), (PG8_LAS unsigned*)(lds + (bufoff) + ldsw + _i * 8192), 16, 0, 0); } while (0)
; #define PG8_LDA(dst, b, h) do { _Pragma("unroll") for (int m = 0; m < 4; ++m) _Pragma("unroll") for (int k = 0; k < 2; ++k) dst[m][k] = *(const PG8_LAS bf16x8*)(lds + PG8_SA(b, h) + aoff + m * 2048 + k * 1024); } while (0)
; #define PG8_LDB(dst, b, h) do { _Pragma("unroll") for (int n = 0; n < 2; ++n) _Pragma("unroll") for (int k = 0; k < 2; ++k) dst[n][k] = *(const PG8_LAS bf16x8*)(lds + PG8_SB(b, h) + boff + n * 2048 + k * 1024); } while (0)
; #define PG8_SCHED __builtin_amdgcn_sched_barrier(0)
;     __host__ __device__ bool next(int i, Unit& u) const {
;         const long L = (long)i * G + c; if (L >= nwg) return false;
;         int wgid = (int)L; { const int q = nwg / NXCD, r = nwg % NXCD, xcd = wgid % NXCD, off = wgid / NXCD; wgid = (xcd < r ? xcd * (q + 1) : r * (q + 1) + (xcd - r) * q) + off; }
; template <class Epi, class Sched, bool ALIGN_EPI = false, bool SP2 = false, bool DUAL = false>
; __device__ __forceinline__ void gemm_phase(PG8_LAS unsigned char* lds, const Gemm g, const Sched& S, const Epi& E) {
;     ...
;         const bool has_next = S.next(ui + 1, nxt);
;     ...
;             PG8_LDB(B0, 0, 0); PG8_LDB(B1, 0, 1); PG8_SCHED; PG8_LDA(At, 0, 0); PG8_STAGE(PG8_SA(1, 1), a1 + hstep, voffA);
.LBB0_1182:
	ds_read_b128 v[128:131], v201
	ds_read_b128 v[132:135], v201 offset:1024
	ds_read_b128 v[136:139], v201 offset:2048
	ds_read_b128 v[140:143], v201 offset:3072
	ds_read_b128 v[144:147], v202
	ds_read_b128 v[148:151], v202 offset:1024
	ds_read_b128 v[152:155], v202 offset:2048
	ds_read_b128 v[156:159], v202 offset:3072
	ds_read_b128 v[160:163], v203
	ds_read_b128 v[182:185], v203 offset:1024
	ds_read_b128 v[186:189], v203 offset:2048
	ds_read_b128 v[190:193], v203 offset:3072
	ds_read_b128 v[204:207], v203 offset:4096
	ds_read_b128 v[208:211], v203 offset:5120
	ds_read_b128 v[212:215], v203 offset:6144
	ds_read_b128 v[216:219], v203 offset:7168
	s_add_i32 s36, s36, 1
	s_mul_i32 s0, s36, s39
	s_mul_hi_u32 s1, s36, s92
	s_add_i32 s1, s1, s0
	s_mul_i32 s0, s36, s92
	s_add_u32 s0, s0, s2
	s_addc_u32 s1, s1, s29
	v_cmp_gt_i64_e32 vcc, s[0:1], v[180:181]
	v_cmp_lt_i64_e64 s[4:5], s[0:1], v[178:179]
	s_cbranch_vccnz .LBB0_1188
	s_ashr_i32 s1, s0, 31
	s_lshr_b32 s1, s1, 29
	s_add_i32 s22, s0, s1
	s_and_b32 s1, s22, -8
	s_sub_i32 s23, s0, s1
	s_cmp_gt_i32 s23, -1
	s_mov_b64 s[0:1], -1
	s_cbranch_scc0 .LBB0_1185
	s_lshl_b32 s26, s23, 7
	s_mov_b64 s[0:1], 0

; #define PG8_STAGE(bufoff, gbase, voff) do { _Pragma("unroll") for (int _i = 0; _i < 2; ++_i) \
;         __builtin_amdgcn_global_load_lds((const unsigned*)((const char*)(gbase) + (voff)[_i]), (PG8_LAS unsigned*)(lds + (bufoff) + ldsw + _i * 8192), 16, 0, 0); } while (0)
; #define PG8_LDA(dst, b, h) do { _Pragma("unroll") for (int m = 0; m < 4; ++m) _Pragma("unroll") for (int k = 0; k < 2; ++k) dst[m][k] = *(const PG8_LAS bf16x8*)(lds + PG8_SA(b, h) + aoff + m * 2048 + k * 1024); } while (0)
; #define PG8_LDB(dst, b, h) do { _Pragma("unroll") for (int n = 0; n < 2; ++n) _Pragma("unroll") for (int k = 0; k < 2; ++k) dst[n][k] = *(const PG8_LAS bf16x8*)(lds + PG8_SB(b, h) + boff + n * 2048 + k * 1024); } while (0)
; #define PG8_WAIT_V(n) asm volatile("s_waitcnt vmcnt(" #n ")" ::: "memory")
; #define PG8_WAIT_L(n) asm volatile("s_waitcnt lgkmcnt(" #n ")" ::: "memory")
; #define PG8_BAR __builtin_amdgcn_s_barrier()
; #define PG8_SCHED __builtin_amdgcn_sched_barrier(0)
; template <class Epi, class Sched, bool ALIGN_EPI = false, bool SP2 = false, bool DUAL = false>
; __device__ __forceinline__ void gemm_phase(PG8_LAS unsigned char* lds, const Gemm g, const Sched& S, const Epi& E) {
;     ...
;             const char* a2 = last ? nA : cA + (size_t)(t + 2) * kstep; const char* b2 = last ? nB : cB + (size_t)(t + 2) * kstep;
;             const char* a3 = a2 + kstep; const char* b3 = b2 + kstep;
;             if (last && has_next) S.a_ready(nxt);
;             if constexpr (SP2) {
;             PG8_LDB(B0, 0, 0); PG8_LDB(B1, 0, 1); PG8_SCHED; PG8_LDA(At, 0, 0); PG8_STAGE(PG8_SA(1, 1), a1 + hstep, voffA);
;             PG8_WAIT_V(8); PG8_WAIT_L(0); PG8_BAR; PG8_MMA(0, 0, At, B0); PG8_MMA(0, 1, At, B1); PG8_BAR; PG8_SCHED;
;             PG8_LDA(At, 0, 1); PG8_STAGE(PG8_SB(0, 0), b2, voffB); PG8_STAGE(PG8_SB(0, 1), b2 + hstep, voffB); PG8_STAGE(PG8_SA(0, 0), a2, voffA);
;             PG8_WAIT_V(8); PG8_WAIT_L(0); PG8_BAR; PG8_MMA(1, 0, At, B0); PG8_MMA(1, 1, At, B1); PG8_BAR; PG8_SCHED;
;     ...
;         if (!keep)
; #pragma unroll
;         for (int a = 0; a < 2; ++a)
; #pragma unroll
;             for (int b = 0; b < 2; ++b)
; #pragma unroll
;                 for (int m = 0; m < 4; ++m)
; #pragma unroll
;                     for (int n = 0; n < 2; ++n) acc[a][b][m][n] = (f32x4){0.f, 0.f, 0.f, 0.f};
.LBB0_1192:
	s_add_u32 s24, s24, 0x160080
	s_addc_u32 s25, s25, 0
	s_add_u32 s46, s14, 0x100
	s_addc_u32 s47, s15, 0
	s_mov_b32 s48, -2
	s_add_u32 s14, s24, 0xffea0080
	s_addc_u32 s15, s25, -1
	s_cmpk_eq_i32 s48, 0x54
	s_cselect_b32 s27, s5, s15
	s_cselect_b32 s26, s4, s14
	s_cselect_b32 s15, s23, s47
	s_cselect_b32 s14, s22, s46
	v_lshl_add_u64 v[220:221], s[24:25], 0, v[172:173]
	s_add_i32 m0, s31, 0xc000
	s_nop 0
	global_load_lds_dwordx4 v[220:221], off
	v_lshl_add_u64 v[220:221], s[24:25], 0, v[174:175]
	s_add_i32 m0, s31, 0xe000
	s_nop 0
	global_load_lds_dwordx4 v[220:221], off
	s_waitcnt vmcnt(8)
	s_waitcnt lgkmcnt(0)
	s_setprio 1
	s_barrier
	v_mfma_f32_16x16x32_bf16 v[124:127], v[128:131], v[160:163], 0
	v_mfma_f32_16x16x32_bf16 v[120:123], v[136:139], v[160:163], 0
	v_mfma_f32_16x16x32_bf16 v[112:115], v[128:131], v[186:189], 0
	v_mfma_f32_16x16x32_bf16 v[104:107], v[136:139], v[186:189], 0
	v_mfma_f32_16x16x32_bf16 v[96:99], v[128:131], v[204:207], 0
	v_mfma_f32_16x16x32_bf16 v[88:91], v[136:139], v[204:207], 0
	v_mfma_f32_16x16x32_bf16 v[80:83], v[128:131], v[212:215], 0
	v_mfma_f32_16x16x32_bf16 v[72:75], v[136:139], v[212:215], 0
	v_mfma_f32_16x16x32_bf16 v[124:127], v[132:135], v[182:185], v[124:127]
	v_mfma_f32_16x16x32_bf16 v[120:123], v[140:143], v[182:185], v[120:123]
	v_mfma_f32_16x16x32_bf16 v[112:115], v[132:135], v[190:193], v[112:115]
	v_mfma_f32_16x16x32_bf16 v[104:107], v[140:143], v[190:193], v[104:107]
	v_mfma_f32_16x16x32_bf16 v[96:99], v[132:135], v[208:211], v[96:99]
	v_mfma_f32_16x16x32_bf16 v[88:91], v[140:143], v[208:211], v[88:91]
	v_mfma_f32_16x16x32_bf16 v[80:83], v[132:135], v[216:219], v[80:83]
	v_mfma_f32_16x16x32_bf16 v[72:75], v[140:143], v[216:219], v[72:75]
	s_setprio 0
	s_setprio 1
	v_mfma_f32_16x16x32_bf16 v[116:119], v[144:147], v[160:163], 0
	v_mfma_f32_16x16x32_bf16 v[108:111], v[152:155], v[160:163], 0
	v_mfma_f32_16x16x32_bf16 v[100:103], v[144:147], v[186:189], 0
	v_mfma_f32_16x16x32_bf16 v[92:95], v[152:155], v[186:189], 0
	v_mfma_f32_16x16x32_bf16 v[84:87], v[144:147], v[204:207], 0
	v_mfma_f32_16x16x32_bf16 v[76:79], v[152:155], v[204:207], 0
	v_mfma_f32_16x16x32_bf16 v[68:71], v[144:147], v[212:215], 0
	v_mfma_f32_16x16x32_bf16 v[64:67], v[152:155], v[212:215], 0
	v_mfma_f32_16x16x32_bf16 v[116:119], v[148:151], v[182:185], v[116:119]
	v_mfma_f32_16x16x32_bf16 v[108:111], v[156:159], v[182:185], v[108:111]
	v_mfma_f32_16x16x32_bf16 v[100:103], v[148:151], v[190:193], v[100:103]
	v_mfma_f32_16x16x32_bf16 v[92:95], v[156:159], v[190:193], v[92:95]
	v_mfma_f32_16x16x32_bf16 v[84:87], v[148:151], v[208:211], v[84:87]
	v_mfma_f32_16x16x32_bf16 v[76:79], v[156:159], v[208:211], v[76:79]
	v_mfma_f32_16x16x32_bf16 v[68:71], v[148:151], v[216:219], v[68:71]
	v_mfma_f32_16x16x32_bf16 v[64:67], v[156:159], v[216:219], v[64:67]
	s_barrier
	s_setprio 0
	s_add_i32 s49, s40, s30
	v_lshl_add_u64 v[220:221], s[14:15], 0, v[166:167]
	s_mov_b32 m0, s49
	ds_read_b128 v[160:163], v203 offset:16384
	ds_read_b128 v[182:185], v203 offset:17408
	ds_read_b128 v[186:189], v203 offset:18432
	ds_read_b128 v[190:193], v203 offset:19456
	ds_read_b128 v[204:207], v203 offset:20480
	ds_read_b128 v[208:211], v203 offset:21504
	ds_read_b128 v[212:215], v203 offset:22528
	ds_read_b128 v[216:219], v203 offset:23552
	global_load_lds_dwordx4 v[220:221], off
	s_add_i32 m0, s49, 0x2000
	s_add_u32 s50, s14, 0x160000
	v_lshl_add_u64 v[222:223], s[14:15], 0, v[170:171]
	s_addc_u32 s51, s15, 0
	s_add_i32 s49, s41, s30
	global_load_lds_dwordx4 v[222:223], off
	v_lshl_add_u64 v[224:225], s[50:51], 0, v[166:167]
	s_mov_b32 m0, s49
	v_lshl_add_u64 v[226:227], s[26:27], 0, v[168:169]
	global_load_lds_dwordx4 v[224:225], off
	v_lshl_add_u64 v[224:225], s[50:51], 0, v[170:171]
	s_add_i32 m0, s49, 0x2000
	s_nop 0
	global_load_lds_dwordx4 v[224:225], off
	v_lshl_add_u64 v[224:225], s[26:27], 0, v[164:165]
	s_mov_b32 m0, s31
	s_nop 0
	global_load_lds_dwordx4 v[224:225], off
	s_mov_b32 m0, s33
	s_nop 0
	global_load_lds_dwordx4 v[226:227], off
	s_waitcnt vmcnt(8)
	s_waitcnt lgkmcnt(0)
	s_setprio 1
	s_barrier
	v_mfma_f32_16x16x32_bf16 v[60:63], v[128:131], v[160:163], 0
	v_mfma_f32_16x16x32_bf16 v[56:59], v[136:139], v[160:163], 0
	v_mfma_f32_16x16x32_bf16 v[48:51], v[128:131], v[186:189], 0
	v_mfma_f32_16x16x32_bf16 v[40:43], v[136:139], v[186:189], 0
	v_mfma_f32_16x16x32_bf16 v[32:35], v[128:131], v[204:207], 0
	v_mfma_f32_16x16x32_bf16 v[24:27], v[136:139], v[204:207], 0
	v_mfma_f32_16x16x32_bf16 v[16:19], v[128:131], v[212:215], 0
	v_mfma_f32_16x16x32_bf16 v[8:11], v[136:139], v[212:215], 0
	v_mfma_f32_16x16x32_bf16 v[60:63], v[132:135], v[182:185], v[60:63]
	v_mfma_f32_16x16x32_bf16 v[56:59], v[140:143], v[182:185], v[56:59]
	v_mfma_f32_16x16x32_bf16 v[48:51], v[132:135], v[190:193], v[48:51]
	v_mfma_f32_16x16x32_bf16 v[40:43], v[140:143], v[190:193], v[40:43]
	v_mfma_f32_16x16x32_bf16 v[32:35], v[132:135], v[208:211], v[32:35]
	v_mfma_f32_16x16x32_bf16 v[24:27], v[140:143], v[208:211], v[24:27]
	v_mfma_f32_16x16x32_bf16 v[16:19], v[132:135], v[216:219], v[16:19]
	v_mfma_f32_16x16x32_bf16 v[8:11], v[140:143], v[216:219], v[8:11]
	s_setprio 0
	s_setprio 1
	v_mfma_f32_16x16x32_bf16 v[52:55], v[144:147], v[160:163], 0
	v_mfma_f32_16x16x32_bf16 v[44:47], v[152:155], v[160:163], 0
	v_mfma_f32_16x16x32_bf16 v[36:39], v[144:147], v[186:189], 0
	v_mfma_f32_16x16x32_bf16 v[28:31], v[152:155], v[186:189], 0
	v_mfma_f32_16x16x32_bf16 v[20:23], v[144:147], v[204:207], 0
	v_mfma_f32_16x16x32_bf16 v[12:15], v[152:155], v[204:207], 0
	v_mfma_f32_16x16x32_bf16 v[4:7], v[144:147], v[212:215], 0
	v_mfma_f32_16x16x32_bf16 v[0:3], v[152:155], v[212:215], 0
	v_mfma_f32_16x16x32_bf16 v[52:55], v[148:151], v[182:185], v[52:55]
	v_mfma_f32_16x16x32_bf16 v[44:47], v[156:159], v[182:185], v[44:47]
	v_mfma_f32_16x16x32_bf16 v[36:39], v[148:151], v[190:193], v[36:39]
	v_mfma_f32_16x16x32_bf16 v[28:31], v[156:159], v[190:193], v[28:31]
	v_mfma_f32_16x16x32_bf16 v[20:23], v[148:151], v[208:211], v[20:23]
	v_mfma_f32_16x16x32_bf16 v[12:15], v[156:159], v[208:211], v[12:15]
	v_mfma_f32_16x16x32_bf16 v[4:7], v[148:151], v[216:219], v[4:7]
	v_mfma_f32_16x16x32_bf16 v[0:3], v[156:159], v[216:219], v[0:3]
	s_barrier
; #define PG8_STAGE(bufoff, gbase, voff) do { _Pragma("unroll") for (int _i = 0; _i < 2; ++_i) \
;         __builtin_amdgcn_global_load_lds((const unsigned*)((const char*)(gbase) + (voff)[_i]), (PG8_LAS unsigned*)(lds + (bufoff) + ldsw + _i * 8192), 16, 0, 0); } while (0)
; #define PG8_LDA(dst, b, h) do { _Pragma("unroll") for (int m = 0; m < 4; ++m) _Pragma("unroll") for (int k = 0; k < 2; ++k) dst[m][k] = *(const PG8_LAS bf16x8*)(lds + PG8_SA(b, h) + aoff + m * 2048 + k * 1024); } while (0)
; #define PG8_LDB(dst, b, h) do { _Pragma("unroll") for (int n = 0; n < 2; ++n) _Pragma("unroll") for (int k = 0; k < 2; ++k) dst[n][k] = *(const PG8_LAS bf16x8*)(lds + PG8_SB(b, h) + boff + n * 2048 + k * 1024); } while (0)
; #define PG8_MMA(ai, bj, At, Bt) do { __builtin_amdgcn_s_setprio(1); _Pragma("unroll") for (int m = 0; m < 4; ++m) _Pragma("unroll") for (int n = 0; n < 2; ++n) _Pragma("unroll") for (int k = 0; k < 2; ++k) \
;         acc[ai][bj][m][n] = __builtin_amdgcn_mfma_f32_16x16x32_bf16(Bt[n][k], At[m][k], acc[ai][bj][m][n], 0, 0, 0); __builtin_amdgcn_s_setprio(0); } while (0)
; #define PG8_WAIT_V(n) asm volatile("s_waitcnt vmcnt(" #n ")" ::: "memory")
; #define PG8_WAIT_L(n) asm volatile("s_waitcnt lgkmcnt(" #n ")" ::: "memory")
; #define PG8_BAR __builtin_amdgcn_s_barrier()
; #define PG8_SCHED __builtin_amdgcn_sched_barrier(0)
; template <class Epi, class Sched, bool ALIGN_EPI = false, bool SP2 = false, bool DUAL = false>
; __device__ __forceinline__ void gemm_phase(PG8_LAS unsigned char* lds, const Gemm g, const Sched& S, const Epi& E) {
;     ...
;             PG8_LDB(B0, 1, 0); PG8_LDB(B1, 1, 1); PG8_SCHED; PG8_LDA(At, 1, 0); PG8_STAGE(PG8_SA(0, 1), a2 + hstep, voffA);
;             PG8_WAIT_V(8); PG8_WAIT_L(0); PG8_BAR; PG8_MMA(0, 0, At, B0); PG8_MMA(0, 1, At, B1); PG8_BAR; PG8_SCHED;
	s_setprio 0
	s_add_i32 s49, 0, 0x18000
	s_add_i32 s50, 0, 0x1c000
	v_add_u32_e32 v140, s49, v198
	v_add_u32_e32 v156, s50, v198
	ds_read_b128 v[128:131], v140
	ds_read_b128 v[132:135], v140 offset:1024
	ds_read_b128 v[136:139], v140 offset:2048
	ds_read_b128 v[140:143], v140 offset:3072
	ds_read_b128 v[144:147], v156
	ds_read_b128 v[148:151], v156 offset:1024
	ds_read_b128 v[152:155], v156 offset:2048
	ds_read_b128 v[156:159], v156 offset:3072
	s_add_u32 s26, s26, 0x160000
	s_addc_u32 s27, s27, 0
	s_mov_b32 m0, s34
	v_lshl_add_u64 v[228:229], s[26:27], 0, v[164:165]
	ds_read_b128 v[160:163], v203 offset:32768
	ds_read_b128 v[182:185], v203 offset:33792
	ds_read_b128 v[186:189], v203 offset:34816
	ds_read_b128 v[190:193], v203 offset:35840
	ds_read_b128 v[204:207], v203 offset:36864
	ds_read_b128 v[208:211], v203 offset:37888
	ds_read_b128 v[212:215], v203 offset:38912
	ds_read_b128 v[216:219], v203 offset:39936
	global_load_lds_dwordx4 v[228:229], off
	v_lshl_add_u64 v[228:229], s[26:27], 0, v[168:169]
	s_mov_b32 m0, s35
	s_nop 0
	global_load_lds_dwordx4 v[228:229], off
	s_waitcnt vmcnt(8)
	s_waitcnt lgkmcnt(0)
	s_setprio 1
	s_barrier
	v_mfma_f32_16x16x32_bf16 v[124:127], v[128:131], v[160:163], v[124:127]
	v_mfma_f32_16x16x32_bf16 v[120:123], v[136:139], v[160:163], v[120:123]
	v_mfma_f32_16x16x32_bf16 v[112:115], v[128:131], v[186:189], v[112:115]
	v_mfma_f32_16x16x32_bf16 v[104:107], v[136:139], v[186:189], v[104:107]
	v_mfma_f32_16x16x32_bf16 v[96:99], v[128:131], v[204:207], v[96:99]
	v_mfma_f32_16x16x32_bf16 v[88:91], v[136:139], v[204:207], v[88:91]
	v_mfma_f32_16x16x32_bf16 v[80:83], v[128:131], v[212:215], v[80:83]
	v_mfma_f32_16x16x32_bf16 v[72:75], v[136:139], v[212:215], v[72:75]
	v_mfma_f32_16x16x32_bf16 v[124:127], v[132:135], v[182:185], v[124:127]
	v_mfma_f32_16x16x32_bf16 v[120:123], v[140:143], v[182:185], v[120:123]
	v_mfma_f32_16x16x32_bf16 v[112:115], v[132:135], v[190:193], v[112:115]
	v_mfma_f32_16x16x32_bf16 v[104:107], v[140:143], v[190:193], v[104:107]
	v_mfma_f32_16x16x32_bf16 v[96:99], v[132:135], v[208:211], v[96:99]
	v_mfma_f32_16x16x32_bf16 v[88:91], v[140:143], v[208:211], v[88:91]
	v_mfma_f32_16x16x32_bf16 v[80:83], v[132:135], v[216:219], v[80:83]
	v_mfma_f32_16x16x32_bf16 v[72:75], v[140:143], v[216:219], v[72:75]
	s_setprio 0
	s_setprio 1
	v_mfma_f32_16x16x32_bf16 v[116:119], v[144:147], v[160:163], v[116:119]
	v_mfma_f32_16x16x32_bf16 v[108:111], v[152:155], v[160:163], v[108:111]
	v_mfma_f32_16x16x32_bf16 v[100:103], v[144:147], v[186:189], v[100:103]
	v_mfma_f32_16x16x32_bf16 v[92:95], v[152:155], v[186:189], v[92:95]
	v_mfma_f32_16x16x32_bf16 v[84:87], v[144:147], v[204:207], v[84:87]
	v_mfma_f32_16x16x32_bf16 v[76:79], v[152:155], v[204:207], v[76:79]
	v_mfma_f32_16x16x32_bf16 v[68:71], v[144:147], v[212:215], v[68:71]
	v_mfma_f32_16x16x32_bf16 v[64:67], v[152:155], v[212:215], v[64:67]
	v_mfma_f32_16x16x32_bf16 v[116:119], v[148:151], v[182:185], v[116:119]
	v_mfma_f32_16x16x32_bf16 v[108:111], v[156:159], v[182:185], v[108:111]
	v_mfma_f32_16x16x32_bf16 v[100:103], v[148:151], v[190:193], v[100:103]
	v_mfma_f32_16x16x32_bf16 v[92:95], v[156:159], v[190:193], v[92:95]
	v_mfma_f32_16x16x32_bf16 v[84:87], v[148:151], v[208:211], v[84:87]
	v_mfma_f32_16x16x32_bf16 v[76:79], v[156:159], v[208:211], v[76:79]
	v_mfma_f32_16x16x32_bf16 v[68:71], v[148:151], v[216:219], v[68:71]
	v_mfma_f32_16x16x32_bf16 v[64:67], v[156:159], v[216:219], v[64:67]
	s_barrier
; #define PG8_STAGE(bufoff, gbase, voff) do { _Pragma("unroll") for (int _i = 0; _i < 2; ++_i) \
;         __builtin_amdgcn_global_load_lds((const unsigned*)((const char*)(gbase) + (voff)[_i]), (PG8_LAS unsigned*)(lds + (bufoff) + ldsw + _i * 8192), 16, 0, 0); } while (0)
; #define PG8_LDA(dst, b, h) do { _Pragma("unroll") for (int m = 0; m < 4; ++m) _Pragma("unroll") for (int k = 0; k < 2; ++k) dst[m][k] = *(const PG8_LAS bf16x8*)(lds + PG8_SA(b, h) + aoff + m * 2048 + k * 1024); } while (0)
; #define PG8_MMA(ai, bj, At, Bt) do { __builtin_amdgcn_s_setprio(1); _Pragma("unroll") for (int m = 0; m < 4; ++m) _Pragma("unroll") for (int n = 0; n < 2; ++n) _Pragma("unroll") for (int k = 0; k < 2; ++k) \
;         acc[ai][bj][m][n] = __builtin_amdgcn_mfma_f32_16x16x32_bf16(Bt[n][k], At[m][k], acc[ai][bj][m][n], 0, 0, 0); __builtin_amdgcn_s_setprio(0); } while (0)
; #define PG8_WAIT_V(n) asm volatile("s_waitcnt vmcnt(" #n ")" ::: "memory")
; #define PG8_WAIT_L(n) asm volatile("s_waitcnt lgkmcnt(" #n ")" ::: "memory")
; #define PG8_BAR __builtin_amdgcn_s_barrier()
; #define PG8_SCHED __builtin_amdgcn_sched_barrier(0)
; template <class Epi, class Sched, bool ALIGN_EPI = false, bool SP2 = false, bool DUAL = false>
; __device__ __forceinline__ void gemm_phase(PG8_LAS unsigned char* lds, const Gemm g, const Sched& S, const Epi& E) {
;     ...
;             PG8_LDA(At, 1, 1); PG8_STAGE(PG8_SB(1, 0), b3, voffB); PG8_STAGE(PG8_SB(1, 1), b3 + hstep, voffB); PG8_STAGE(PG8_SA(1, 0), a3, voffA);
;             PG8_WAIT_V(8); PG8_WAIT_L(0); PG8_BAR; PG8_MMA(1, 0, At, B0); PG8_MMA(1, 1, At, B1); PG8_BAR; PG8_SCHED;
	s_setprio 0
	s_add_i32 s26, s49, s30
	v_lshl_add_u64 v[220:221], v[220:221], 0, s[18:19]
	s_mov_b32 m0, s26
	ds_read_b128 v[160:163], v203 offset:49152
	ds_read_b128 v[182:185], v203 offset:50176
	ds_read_b128 v[186:189], v203 offset:51200
	ds_read_b128 v[190:193], v203 offset:52224
	ds_read_b128 v[204:207], v203 offset:53248
	ds_read_b128 v[208:211], v203 offset:54272
	ds_read_b128 v[212:215], v203 offset:55296
	ds_read_b128 v[216:219], v203 offset:56320
	global_load_lds_dwordx4 v[220:221], off
	s_add_i32 m0, s26, 0x2000
	s_add_u32 s14, s14, 0x160080
	v_lshl_add_u64 v[220:221], v[222:223], 0, s[18:19]
	s_addc_u32 s15, s15, 0
	s_add_i32 s26, s50, s30
	global_load_lds_dwordx4 v[220:221], off
	v_lshl_add_u64 v[220:221], s[14:15], 0, v[166:167]
	s_mov_b32 m0, s26
	s_nop 0
	global_load_lds_dwordx4 v[220:221], off
	v_lshl_add_u64 v[220:221], s[14:15], 0, v[170:171]
	s_add_i32 m0, s26, 0x2000
	s_nop 0
	global_load_lds_dwordx4 v[220:221], off
	v_lshl_add_u64 v[220:221], v[224:225], 0, s[18:19]
	s_mov_b32 m0, s37
	s_nop 0
	global_load_lds_dwordx4 v[220:221], off
	v_lshl_add_u64 v[220:221], v[226:227], 0, s[18:19]
	s_mov_b32 m0, s38
	s_nop 0
	global_load_lds_dwordx4 v[220:221], off
	s_waitcnt vmcnt(8)
	s_waitcnt lgkmcnt(0)
	s_setprio 1
	s_barrier
	v_mfma_f32_16x16x32_bf16 v[60:63], v[128:131], v[160:163], v[60:63]
	v_mfma_f32_16x16x32_bf16 v[56:59], v[136:139], v[160:163], v[56:59]
	v_mfma_f32_16x16x32_bf16 v[48:51], v[128:131], v[186:189], v[48:51]
	v_mfma_f32_16x16x32_bf16 v[40:43], v[136:139], v[186:189], v[40:43]
	v_mfma_f32_16x16x32_bf16 v[32:35], v[128:131], v[204:207], v[32:35]
	v_mfma_f32_16x16x32_bf16 v[24:27], v[136:139], v[204:207], v[24:27]
	v_mfma_f32_16x16x32_bf16 v[16:19], v[128:131], v[212:215], v[16:19]
	v_mfma_f32_16x16x32_bf16 v[8:11], v[136:139], v[212:215], v[8:11]
	v_mfma_f32_16x16x32_bf16 v[60:63], v[132:135], v[182:185], v[60:63]
	v_mfma_f32_16x16x32_bf16 v[56:59], v[140:143], v[182:185], v[56:59]
	v_mfma_f32_16x16x32_bf16 v[48:51], v[132:135], v[190:193], v[48:51]
	v_mfma_f32_16x16x32_bf16 v[40:43], v[140:143], v[190:193], v[40:43]
	v_mfma_f32_16x16x32_bf16 v[32:35], v[132:135], v[208:211], v[32:35]
	v_mfma_f32_16x16x32_bf16 v[24:27], v[140:143], v[208:211], v[24:27]
	v_mfma_f32_16x16x32_bf16 v[16:19], v[132:135], v[216:219], v[16:19]
	v_mfma_f32_16x16x32_bf16 v[8:11], v[140:143], v[216:219], v[8:11]
	s_setprio 0
	s_setprio 1
	v_mfma_f32_16x16x32_bf16 v[52:55], v[144:147], v[160:163], v[52:55]
	v_mfma_f32_16x16x32_bf16 v[44:47], v[152:155], v[160:163], v[44:47]
	v_mfma_f32_16x16x32_bf16 v[36:39], v[144:147], v[186:189], v[36:39]
	v_mfma_f32_16x16x32_bf16 v[28:31], v[152:155], v[186:189], v[28:31]
	v_mfma_f32_16x16x32_bf16 v[20:23], v[144:147], v[204:207], v[20:23]
	v_mfma_f32_16x16x32_bf16 v[12:15], v[152:155], v[204:207], v[12:15]
	v_mfma_f32_16x16x32_bf16 v[4:7], v[144:147], v[212:215], v[4:7]
	v_mfma_f32_16x16x32_bf16 v[0:3], v[152:155], v[212:215], v[0:3]
	v_mfma_f32_16x16x32_bf16 v[52:55], v[148:151], v[182:185], v[52:55]
	v_mfma_f32_16x16x32_bf16 v[44:47], v[156:159], v[182:185], v[44:47]
	v_mfma_f32_16x16x32_bf16 v[36:39], v[148:151], v[190:193], v[36:39]
	v_mfma_f32_16x16x32_bf16 v[28:31], v[156:159], v[190:193], v[28:31]
	v_mfma_f32_16x16x32_bf16 v[20:23], v[148:151], v[208:211], v[20:23]
	v_mfma_f32_16x16x32_bf16 v[12:15], v[156:159], v[208:211], v[12:15]
	v_mfma_f32_16x16x32_bf16 v[4:7], v[148:151], v[216:219], v[4:7]
	v_mfma_f32_16x16x32_bf16 v[0:3], v[156:159], v[216:219], v[0:3]
	s_barrier
	s_setprio 0
	s_add_i32 s48, s48, 2
	s_add_u32 s24, s24, 0x100
	s_addc_u32 s25, s25, 0
	s_add_u32 s46, s46, 0x100
	s_addc_u32 s47, s47, 0
